# gate/up epilogue rewritten by hand: conv taps as v_fmac_dpp with lane-masked weights, one halo load per unit (early for sample tiles), sigmoid of block b interleaved with conv of block b+1, scalar-bas
# speedup vs baseline: 1.0172x; 1.0125x over previous
; #define LAS __attribute__((address_space(3)))
;     DI void operator()(const AccT& acc, const Unit& u, int wr, int wc, int fr, int fq, LAS unsigned char* ldsx) const {
;     ...
;         for (int n = 0; n < 2; ++n) { const int f = u.pn * 128 + wc * 32 + 16 * n + 4 * fq;
;             w0[n] = *(const f32x4*)(convw + f); w1[n] = *(const f32x4*)(convw + DFF + f); w2[n] = *(const f32x4*)(convw + 2 * DFF + f); cb[n] = *(const f32x4*)(convb + f); }
;         float rs[2][4];
; #pragma unroll
;         for (int ai = 0; ai < 2; ++ai)
; #pragma unroll
;             for (int m = 0; m < 4; ++m) { const int tok = tok0 + 128 * ai + 16 * m; const bool ok = tok >= 0 && tok < (prompt ? SEQ : MTOK);
;                 rs[ai][m] = ok ? rsqrtf(sumsq[ok ? tok : 0] * (1.f / DM) + EPS) : 0.f; }
;     ...
;                 const int sb = 4 * (T - GU_PT) + 2 * ai + wr;
;                 if (prompt) {
;                     if (ai | wr) { const int sai = wr ? ai : ai - 1, swr = wr ^ 1; const LAS float* hp = H + ((sai * 2 + swr) * 4 + wc) * 64 + 16 * n + 4 * fq;
;                         hm2 = *(const LAS f32x4*)hp; hm1 = *(const LAS f32x4*)(hp + 32); }
;                 } else { hm2 = *(const f32x4*)(state + (size_t)(sb * 2) * DFF + f); hm1 = *(const f32x4*)(state + (size_t)(sb * 2 + 1) * DFF + f); }
.LBB0_833:
	v_lshl_or_b32 v216, s28, 7, v244
	v_ashrrev_i32_e32 v217, 31, v216
	v_lshlrev_b64 v[196:197], 2, v[216:217]
	v_or_b32_e32 v182, 16, v216
	v_lshl_add_u64 v[46:47], s[10:11], 0, v[196:197]
	v_lshl_add_u64 v[48:49], s[12:13], 0, v[196:197]
	v_ashrrev_i32_e32 v183, 31, v182
	global_load_dwordx4 v[124:127], v[46:47], off
	global_load_dwordx4 v[128:131], v[48:49], off
	v_lshlrev_b64 v[48:49], 2, v[182:183]
	v_lshl_add_u64 v[44:45], s[48:49], 0, v[196:197]
	v_lshl_add_u64 v[56:57], s[50:51], 0, v[196:197]
	v_lshl_add_u64 v[50:51], s[10:11], 0, v[48:49]
	v_lshl_add_u64 v[52:53], s[12:13], 0, v[48:49]
	global_load_dwordx4 v[132:135], v[44:45], off
	s_nop 0
	global_load_dwordx4 v[44:47], v[44:45], off offset:64
	s_nop 0
	global_load_dwordx4 v[48:51], v[50:51], off
	s_nop 0
	global_load_dwordx4 v[52:55], v[52:53], off
	s_nop 0
	global_load_dwordx4 v[136:139], v[56:57], off
	s_nop 0
	global_load_dwordx4 v[56:59], v[56:57], off offset:64
	s_and_b64 vcc, exec, s[60:61]
	s_cbranch_vccz .Lgu_nosamp
	v_and_b32_e32 v160, 15, v240
	v_lshrrev_b32_e32 v161, 2, v160
	v_and_b32_e32 v162, 1, v161
	v_lshrrev_b32_e32 v161, 1, v161
	v_and_b32_e32 v160, 3, v160
	v_xor_b32_e32 v160, 2, v160
	v_min_u32_e32 v160, 1, v160
	s_lshl_b32 s31, s42, 2
	s_add_i32 s31, s36, s31
	s_lshl_b32 s31, s31, 1
	v_lshl_add_u32 v160, v162, 2, v160
	v_add_u32_e32 v160, s31, v160
	v_mul_u32_u24_e32 v160, 0x2c00, v160
	v_lshl_add_u32 v160, v161, 6, v160
	v_add_u32_e32 v160, v196, v160
	global_load_dwordx4 v[248:251], v160, s[4:5]
.Lgu_nosamp:
	v_add_u32_e32 v172, s29, v240
	v_cmp_gt_u32_e32 vcc, s23, v172
	v_mov_b32_e32 v210, 0
	v_mov_b32_e32 v214, 0
	s_and_saveexec_b64 s[28:29], vcc
	s_cbranch_execz .LBB0_835
	v_lshl_add_u64 v[160:161], v[172:173], 2, s[58:59]
	global_load_dword v214, v[160:161], off

; #define LAS __attribute__((address_space(3)))
;     DI void operator()(const AccT& acc, const Unit& u, int wr, int wc, int fr, int fq, LAS unsigned char* ldsx) const {
;     ...
;         for (int n = 0; n < 2; ++n) {
;             const int f = u.pn * 128 + wc * 32 + 16 * n + 4 * fq;
; #pragma unroll
;             for (int ai = 0; ai < 2; ++ai) {
;                 f32x4 hm1 = {0.f, 0.f, 0.f, 0.f}, hm2 = {0.f, 0.f, 0.f, 0.f};
;                 const int sb = 4 * (T - GU_PT) + 2 * ai + wr;
;                 if (prompt) {
;                     if (ai | wr) { const int sai = wr ? ai : ai - 1, swr = wr ^ 1; const LAS float* hp = H + ((sai * 2 + swr) * 4 + wc) * 64 + 16 * n + 4 * fq;
;                         hm2 = *(const LAS f32x4*)hp; hm1 = *(const LAS f32x4*)(hp + 32); }
;                 } else { hm2 = *(const f32x4*)(state + (size_t)(sb * 2) * DFF + f); hm1 = *(const f32x4*)(state + (size_t)(sb * 2 + 1) * DFF + f); }
;                 f32x4 p1 = hm1, p2;
; #pragma unroll
;                 for (int j = 0; j < 4; ++j) p2[j] = fr == 1 ? hm1[j] : hm2[j];
; #pragma unroll
;                 for (int m = 0; m < 4; ++m) {
;                     const f32x4 g = acc[ai][0][m][n] * rs[ai][m];
;                     f32x4 gm1, gm2;
; #pragma unroll
;                     for (int j = 0; j < 4; ++j) {
;                         gm1[j] = __int_as_float(__builtin_amdgcn_update_dpp(__float_as_int(p1[j]), __float_as_int(g[j]), 0x111, 0xf, 0xf, false));
;                         gm2[j] = __int_as_float(__builtin_amdgcn_update_dpp(__float_as_int(p2[j]), __float_as_int(g[j]), 0x112, 0xf, 0xf, false));
;                         if (m < 3) {
;                             p1[j] = __int_as_float(__builtin_amdgcn_update_dpp(0, __float_as_int(g[j]), 0x121, 0xf, 0xf, false));
;                             p2[j] = __int_as_float(__builtin_amdgcn_update_dpp(0, __float_as_int(g[j]), 0x122, 0xf, 0xf, false)); }
;                     }
;                     const f32x4 cv = cb[n] + w0[n] * gm2 + w1[n] * gm1 + w2[n] * g;
;                     const f32x4 up = acc[ai][1][m][n] * rs[ai][m];
;                     f32x4 y;
; #pragma unroll
;                     for (int j = 0; j < 4; ++j) y[j] = cv[j] * __builtin_amdgcn_rcpf(1.f + __builtin_amdgcn_exp2f(-cv[j] * LOG2E)) * up[j];
;                     const int tok = tok0 + 128 * ai + 16 * m;
;                     bool ok = true;
.LBB0_853:
	s_cmp_lg_u32 s42, 64
	s_cselect_b64 s[98:99], -1, 0
	v_and_b32_e32 v212, 15, v240
	v_mov_b32_e32 v185, 0xbfb8aa3b
	v_cmp_eq_u32_e64 s[94:95], 0, v212
	v_cmp_gt_u32_e64 s[96:97], 2, v212
	s_movk_i32 s76, 0x4000
	v_cmp_gt_i32_e32 vcc, s76, v172
	s_or_b64 s[60:61], s[98:99], vcc
	s_movk_i32 s76, 0x3ff0
	v_cmp_gt_i32_e32 vcc, s76, v172
	s_or_b64 s[62:63], s[98:99], vcc
	s_movk_i32 s76, 0x3fe0
	v_cmp_gt_i32_e32 vcc, s76, v172
	s_or_b64 s[64:65], s[98:99], vcc
	s_movk_i32 s76, 0x3fd0
	v_cmp_gt_i32_e32 vcc, s76, v172
	s_or_b64 s[66:67], s[98:99], vcc
	s_movk_i32 s76, 0x3f80
	v_cmp_gt_i32_e32 vcc, s76, v172
	s_or_b64 s[68:69], s[98:99], vcc
	s_movk_i32 s76, 0x3f70
	v_cmp_gt_i32_e32 vcc, s76, v172
	s_or_b64 s[70:71], s[98:99], vcc
	s_movk_i32 s76, 0x3f60
	v_cmp_gt_i32_e32 vcc, s76, v172
	s_or_b64 s[72:73], s[98:99], vcc
	s_movk_i32 s76, 0x3f50
	v_cmp_gt_i32_e32 vcc, s76, v172
	s_or_b64 s[74:75], s[98:99], vcc
	s_cmp_gt_i32 s42, 64
	s_cbranch_scc1 .Lgu_samp0
	s_and_b64 s[60:61], s[60:61], s[20:21]
	v_readlane_b32 s0, v252, 40
	v_lshrrev_b32_e32 v186, 2, v212
	v_and_b32_e32 v187, 1, v186
	v_lshrrev_b32_e32 v186, 1, v186
	v_and_b32_e32 v188, 3, v212
	v_xor_b32_e32 v188, 2, v188
	v_min_u32_e32 v188, 1, v188
	v_cmp_eq_u32_e32 vcc, 1, v187
	v_add_u32_e32 v189, s0, v243
	v_mov_b32_e32 v248, 0
	v_mov_b32_e32 v249, 0
	v_cndmask_b32_e32 v189, v189, v247, vcc
	v_mov_b32_e32 v250, 0
	v_mov_b32_e32 v251, 0
	v_lshl_add_u32 v189, v186, 6, v189
	v_lshl_add_u32 v189, v188, 7, v189
	s_or_b64 s[30:31], vcc, s[16:17]
	s_and_saveexec_b64 s[28:29], s[30:31]
	ds_read_b128 v[248:251], v189
	s_mov_b64 exec, s[28:29]
.Lgu_samp0:
	v_add_u32_e32 v213, 16, v172
	s_add_u32 s46, s54, 0xfffea000
	s_addc_u32 s47, s55, -1
	v_mul_lo_u32 v213, v213, s87
	v_cndmask_b32_e64 v160, 0, v124, s[94:95]
	v_cndmask_b32_e64 v124, v124, 0, s[94:95]
	v_cndmask_b32_e64 v164, 0, v132, s[96:97]
	v_cndmask_b32_e64 v132, v132, 0, s[96:97]
	v_cndmask_b32_e64 v161, 0, v125, s[94:95]
	v_cndmask_b32_e64 v125, v125, 0, s[94:95]
	v_cndmask_b32_e64 v165, 0, v133, s[96:97]
	v_cndmask_b32_e64 v133, v133, 0, s[96:97]
	v_cndmask_b32_e64 v162, 0, v126, s[94:95]
	v_cndmask_b32_e64 v126, v126, 0, s[94:95]
	v_cndmask_b32_e64 v166, 0, v134, s[96:97]
	v_cndmask_b32_e64 v134, v134, 0, s[96:97]
	v_cndmask_b32_e64 v163, 0, v127, s[94:95]
	v_cndmask_b32_e64 v127, v127, 0, s[94:95]
	v_cndmask_b32_e64 v167, 0, v135, s[96:97]
	v_cndmask_b32_e64 v135, v135, 0, s[96:97]
	v_add_lshl_u32 v213, v213, v216, 1
	v_pk_mul_f32 v[156:157], v[156:157], v[214:215] op_sel_hi:[1,0]
	v_pk_mul_f32 v[158:159], v[158:159], v[214:215] op_sel_hi:[1,0]
	v_pk_mul_f32 v[152:153], v[152:153], v[214:215] op_sel_hi:[1,0]
	v_pk_mul_f32 v[154:155], v[154:155], v[214:215] op_sel_hi:[1,0]
	v_pk_fma_f32 v[218:219], v[128:129], v[156:157], v[136:137]
	v_pk_fma_f32 v[220:221], v[130:131], v[158:159], v[138:139]
	v_fmac_f32_dpp v218, v156, v124 row_ror:1 row_mask:0xf bank_mask:0xf
	v_fmac_f32_dpp v219, v157, v125 row_ror:1 row_mask:0xf bank_mask:0xf
	v_fmac_f32_dpp v220, v158, v126 row_ror:1 row_mask:0xf bank_mask:0xf
	v_fmac_f32_dpp v221, v159, v127 row_ror:1 row_mask:0xf bank_mask:0xf
	v_fmac_f32_dpp v218, v156, v132 row_ror:2 row_mask:0xf bank_mask:0xf
	v_fmac_f32_dpp v219, v157, v133 row_ror:2 row_mask:0xf bank_mask:0xf
	v_fmac_f32_dpp v220, v158, v134 row_ror:2 row_mask:0xf bank_mask:0xf
	v_fmac_f32_dpp v221, v159, v135 row_ror:2 row_mask:0xf bank_mask:0xf
	s_waitcnt lgkmcnt(0)
	v_fmac_f32_e32 v218, v248, v160
	v_fmac_f32_e32 v219, v249, v161
	v_fmac_f32_e32 v220, v250, v162
	v_fmac_f32_e32 v221, v251, v163
	v_fmac_f32_dpp v218, v248, v164 row_ror:14 row_mask:0xf bank_mask:0xf
	v_fmac_f32_dpp v219, v249, v165 row_ror:14 row_mask:0xf bank_mask:0xf
	v_fmac_f32_dpp v220, v250, v166 row_ror:14 row_mask:0xf bank_mask:0xf
	v_fmac_f32_dpp v221, v251, v167 row_ror:14 row_mask:0xf bank_mask:0xf
	v_pk_mul_f32 v[204:205], v[218:219], v[184:185] op_sel:[0,1] op_sel_hi:[1,1]
	v_pk_mul_f32 v[148:149], v[148:149], v[210:211] op_sel_hi:[1,0]
	v_pk_mul_f32 v[206:207], v[220:221], v[184:185] op_sel:[0,1] op_sel_hi:[1,1]
	v_pk_mul_f32 v[150:151], v[150:151], v[210:211] op_sel_hi:[1,0]
	v_exp_f32_e32 v204, v204
	v_pk_mul_f32 v[144:145], v[144:145], v[210:211] op_sel_hi:[1,0]
	v_exp_f32_e32 v205, v205
	v_pk_mul_f32 v[146:147], v[146:147], v[210:211] op_sel_hi:[1,0]
	v_exp_f32_e32 v206, v206
	v_pk_fma_f32 v[222:223], v[128:129], v[148:149], v[136:137]
	v_exp_f32_e32 v207, v207
	v_pk_fma_f32 v[224:225], v[130:131], v[150:151], v[138:139]
	v_pk_add_f32 v[204:205], v[204:205], 1.0 op_sel_hi:[1,0]
	v_fmac_f32_dpp v222, v148, v124 row_ror:1 row_mask:0xf bank_mask:0xf
	v_pk_add_f32 v[206:207], v[206:207], 1.0 op_sel_hi:[1,0]
	v_fmac_f32_dpp v223, v149, v125 row_ror:1 row_mask:0xf bank_mask:0xf
	v_rcp_f32_e32 v204, v204
	v_fmac_f32_dpp v224, v150, v126 row_ror:1 row_mask:0xf bank_mask:0xf
	v_rcp_f32_e32 v205, v205
	v_fmac_f32_dpp v225, v151, v127 row_ror:1 row_mask:0xf bank_mask:0xf
	v_rcp_f32_e32 v206, v206
	v_fmac_f32_dpp v222, v148, v132 row_ror:2 row_mask:0xf bank_mask:0xf
	v_rcp_f32_e32 v207, v207
	v_fmac_f32_dpp v223, v149, v133 row_ror:2 row_mask:0xf bank_mask:0xf
	v_pk_mul_f32 v[218:219], v[218:219], v[204:205]
	v_fmac_f32_dpp v224, v150, v134 row_ror:2 row_mask:0xf bank_mask:0xf
	v_pk_mul_f32 v[220:221], v[220:221], v[206:207]
	v_fmac_f32_dpp v225, v151, v135 row_ror:2 row_mask:0xf bank_mask:0xf
	v_pk_mul_f32 v[152:153], v[152:153], v[218:219]
	v_fmac_f32_dpp v222, v156, v160 row_ror:1 row_mask:0xf bank_mask:0xf
	v_pk_mul_f32 v[154:155], v[154:155], v[220:221]
	v_fmac_f32_dpp v223, v157, v161 row_ror:1 row_mask:0xf bank_mask:0xf
	v_cvt_pk_bf16_f32 v152, v152, v153
; DI u32x2 pk4(f32x4 v) { u32x2 r; r.x = pk2(v[0], v[1]); r.y = pk2(v[2], v[3]); return r; }
;     DI void operator()(const AccT& acc, const Unit& u, int wr, int wc, int fr, int fq, LAS unsigned char* ldsx) const {
;     ...
;                 for (int m = 0; m < 4; ++m) {
;                     const f32x4 g = acc[ai][0][m][n] * rs[ai][m];
;                     f32x4 gm1, gm2;
; #pragma unroll
;                     for (int j = 0; j < 4; ++j) {
;                         gm1[j] = __int_as_float(__builtin_amdgcn_update_dpp(__float_as_int(p1[j]), __float_as_int(g[j]), 0x111, 0xf, 0xf, false));
;                         gm2[j] = __int_as_float(__builtin_amdgcn_update_dpp(__float_as_int(p2[j]), __float_as_int(g[j]), 0x112, 0xf, 0xf, false));
;                         if (m < 3) {
;                             p1[j] = __int_as_float(__builtin_amdgcn_update_dpp(0, __float_as_int(g[j]), 0x121, 0xf, 0xf, false));
;                             p2[j] = __int_as_float(__builtin_amdgcn_update_dpp(0, __float_as_int(g[j]), 0x122, 0xf, 0xf, false)); }
;                     }
;                     const f32x4 cv = cb[n] + w0[n] * gm2 + w1[n] * gm1 + w2[n] * g;
;                     const f32x4 up = acc[ai][1][m][n] * rs[ai][m];
;                     f32x4 y;
; #pragma unroll
;                     for (int j = 0; j < 4; ++j) y[j] = cv[j] * __builtin_amdgcn_rcpf(1.f + __builtin_amdgcn_exp2f(-cv[j] * LOG2E)) * up[j];
;                     const int tok = tok0 + 128 * ai + 16 * m;
;                     bool ok = true;
;                     if (prompt && ai == 0 && m == 0) ok = (64 * wr + fr) >= 2;
;                     if (lastT) ok = ok && tok < SEQ;
;                     if (ok) *(u32x2*)(Y + ((unsigned)tok * (unsigned)DFF + (unsigned)f)) = pk4(y);
	v_fmac_f32_dpp v224, v158, v162 row_ror:1 row_mask:0xf bank_mask:0xf
	v_cvt_pk_bf16_f32 v153, v154, v155
	v_fmac_f32_dpp v225, v159, v163 row_ror:1 row_mask:0xf bank_mask:0xf
	v_fmac_f32_dpp v222, v156, v164 row_ror:2 row_mask:0xf bank_mask:0xf
	v_fmac_f32_dpp v223, v157, v165 row_ror:2 row_mask:0xf bank_mask:0xf
	v_fmac_f32_dpp v224, v158, v166 row_ror:2 row_mask:0xf bank_mask:0xf
	v_fmac_f32_dpp v225, v159, v167 row_ror:2 row_mask:0xf bank_mask:0xf
	s_and_saveexec_b64 s[28:29], s[60:61]
	global_store_dwordx2 v213, v[152:153], s[46:47]
	s_mov_b64 exec, s[28:29]
	s_add_u32 s46, s46, 0x16000
	s_addc_u32 s47, s47, 0
	v_pk_mul_f32 v[204:205], v[222:223], v[184:185] op_sel:[0,1] op_sel_hi:[1,1]
	v_pk_mul_f32 v[140:141], v[140:141], v[208:209] op_sel_hi:[1,0]
	v_pk_mul_f32 v[206:207], v[224:225], v[184:185] op_sel:[0,1] op_sel_hi:[1,1]
	v_pk_mul_f32 v[142:143], v[142:143], v[208:209] op_sel_hi:[1,0]
	v_exp_f32_e32 v204, v204
	v_pk_mul_f32 v[120:121], v[120:121], v[208:209] op_sel_hi:[1,0]
	v_exp_f32_e32 v205, v205
	v_pk_mul_f32 v[122:123], v[122:123], v[208:209] op_sel_hi:[1,0]
	v_exp_f32_e32 v206, v206
	v_pk_fma_f32 v[218:219], v[128:129], v[140:141], v[136:137]
	v_exp_f32_e32 v207, v207
	v_pk_fma_f32 v[220:221], v[130:131], v[142:143], v[138:139]
	v_pk_add_f32 v[204:205], v[204:205], 1.0 op_sel_hi:[1,0]
	v_fmac_f32_dpp v218, v140, v124 row_ror:1 row_mask:0xf bank_mask:0xf
	v_pk_add_f32 v[206:207], v[206:207], 1.0 op_sel_hi:[1,0]
	v_fmac_f32_dpp v219, v141, v125 row_ror:1 row_mask:0xf bank_mask:0xf
	v_rcp_f32_e32 v204, v204
	v_fmac_f32_dpp v220, v142, v126 row_ror:1 row_mask:0xf bank_mask:0xf
	v_rcp_f32_e32 v205, v205
	v_fmac_f32_dpp v221, v143, v127 row_ror:1 row_mask:0xf bank_mask:0xf
	v_rcp_f32_e32 v206, v206
	v_fmac_f32_dpp v218, v140, v132 row_ror:2 row_mask:0xf bank_mask:0xf
	v_rcp_f32_e32 v207, v207
	v_fmac_f32_dpp v219, v141, v133 row_ror:2 row_mask:0xf bank_mask:0xf
	v_pk_mul_f32 v[222:223], v[222:223], v[204:205]
	v_fmac_f32_dpp v220, v142, v134 row_ror:2 row_mask:0xf bank_mask:0xf
	v_pk_mul_f32 v[224:225], v[224:225], v[206:207]
	v_fmac_f32_dpp v221, v143, v135 row_ror:2 row_mask:0xf bank_mask:0xf
	v_pk_mul_f32 v[144:145], v[144:145], v[222:223]
	v_fmac_f32_dpp v218, v148, v160 row_ror:1 row_mask:0xf bank_mask:0xf
	v_pk_mul_f32 v[146:147], v[146:147], v[224:225]
	v_fmac_f32_dpp v219, v149, v161 row_ror:1 row_mask:0xf bank_mask:0xf
	v_cvt_pk_bf16_f32 v144, v144, v145
	v_fmac_f32_dpp v220, v150, v162 row_ror:1 row_mask:0xf bank_mask:0xf
	v_cvt_pk_bf16_f32 v145, v146, v147
	v_fmac_f32_dpp v221, v151, v163 row_ror:1 row_mask:0xf bank_mask:0xf
	v_fmac_f32_dpp v218, v148, v164 row_ror:2 row_mask:0xf bank_mask:0xf
	v_fmac_f32_dpp v219, v149, v165 row_ror:2 row_mask:0xf bank_mask:0xf
	v_fmac_f32_dpp v220, v150, v166 row_ror:2 row_mask:0xf bank_mask:0xf
	v_fmac_f32_dpp v221, v151, v167 row_ror:2 row_mask:0xf bank_mask:0xf
	s_and_saveexec_b64 s[28:29], s[62:63]
	global_store_dwordx2 v213, v[144:145], s[46:47]
	s_mov_b64 exec, s[28:29]
	s_add_u32 s46, s46, 0x16000
	s_addc_u32 s47, s47, 0
	v_pk_mul_f32 v[204:205], v[218:219], v[184:185] op_sel:[0,1] op_sel_hi:[1,1]
	v_pk_mul_f32 v[116:117], v[116:117], v[202:203] op_sel_hi:[1,0]
	v_pk_mul_f32 v[206:207], v[220:221], v[184:185] op_sel:[0,1] op_sel_hi:[1,1]
	v_pk_mul_f32 v[118:119], v[118:119], v[202:203] op_sel_hi:[1,0]
	v_exp_f32_e32 v204, v204
	v_pk_mul_f32 v[112:113], v[112:113], v[202:203] op_sel_hi:[1,0]
	v_exp_f32_e32 v205, v205
	v_pk_mul_f32 v[114:115], v[114:115], v[202:203] op_sel_hi:[1,0]
	v_exp_f32_e32 v206, v206
	v_pk_fma_f32 v[222:223], v[128:129], v[116:117], v[136:137]
	v_exp_f32_e32 v207, v207
	v_pk_fma_f32 v[224:225], v[130:131], v[118:119], v[138:139]
	v_pk_add_f32 v[204:205], v[204:205], 1.0 op_sel_hi:[1,0]
	v_fmac_f32_dpp v222, v116, v124 row_ror:1 row_mask:0xf bank_mask:0xf
	v_pk_add_f32 v[206:207], v[206:207], 1.0 op_sel_hi:[1,0]
	v_fmac_f32_dpp v223, v117, v125 row_ror:1 row_mask:0xf bank_mask:0xf
	v_rcp_f32_e32 v204, v204
	v_fmac_f32_dpp v224, v118, v126 row_ror:1 row_mask:0xf bank_mask:0xf
	v_rcp_f32_e32 v205, v205
	v_fmac_f32_dpp v225, v119, v127 row_ror:1 row_mask:0xf bank_mask:0xf
	v_rcp_f32_e32 v206, v206
	v_fmac_f32_dpp v222, v116, v132 row_ror:2 row_mask:0xf bank_mask:0xf
	v_rcp_f32_e32 v207, v207
	v_fmac_f32_dpp v223, v117, v133 row_ror:2 row_mask:0xf bank_mask:0xf
	v_pk_mul_f32 v[218:219], v[218:219], v[204:205]
	v_fmac_f32_dpp v224, v118, v134 row_ror:2 row_mask:0xf bank_mask:0xf
	v_pk_mul_f32 v[220:221], v[220:221], v[206:207]
	v_fmac_f32_dpp v225, v119, v135 row_ror:2 row_mask:0xf bank_mask:0xf
	v_pk_mul_f32 v[120:121], v[120:121], v[218:219]
	v_fmac_f32_dpp v222, v140, v160 row_ror:1 row_mask:0xf bank_mask:0xf
	v_pk_mul_f32 v[122:123], v[122:123], v[220:221]
	v_fmac_f32_dpp v223, v141, v161 row_ror:1 row_mask:0xf bank_mask:0xf
	v_cvt_pk_bf16_f32 v120, v120, v121
	v_fmac_f32_dpp v224, v142, v162 row_ror:1 row_mask:0xf bank_mask:0xf
	v_cvt_pk_bf16_f32 v121, v122, v123
	v_fmac_f32_dpp v225, v143, v163 row_ror:1 row_mask:0xf bank_mask:0xf
	v_fmac_f32_dpp v222, v140, v164 row_ror:2 row_mask:0xf bank_mask:0xf
	v_fmac_f32_dpp v223, v141, v165 row_ror:2 row_mask:0xf bank_mask:0xf
	v_fmac_f32_dpp v224, v142, v166 row_ror:2 row_mask:0xf bank_mask:0xf
	v_fmac_f32_dpp v225, v143, v167 row_ror:2 row_mask:0xf bank_mask:0xf
	s_and_saveexec_b64 s[28:29], s[64:65]
	global_store_dwordx2 v213, v[120:121], s[46:47]
	s_mov_b64 exec, s[28:29]
	s_add_u32 s46, s46, 0x16000
	s_addc_u32 s47, s47, 0
	v_pk_mul_f32 v[204:205], v[222:223], v[184:185] op_sel:[0,1] op_sel_hi:[1,1]
	v_pk_mul_f32 v[108:109], v[108:109], v[200:201] op_sel_hi:[1,0]
	v_pk_mul_f32 v[206:207], v[224:225], v[184:185] op_sel:[0,1] op_sel_hi:[1,1]
; DI u32x2 pk4(f32x4 v) { u32x2 r; r.x = pk2(v[0], v[1]); r.y = pk2(v[2], v[3]); return r; }
;     DI void operator()(const AccT& acc, const Unit& u, int wr, int wc, int fr, int fq, LAS unsigned char* ldsx) const {
;     ...
;                 for (int m = 0; m < 4; ++m) {
;                     const f32x4 g = acc[ai][0][m][n] * rs[ai][m];
;                     f32x4 gm1, gm2;
; #pragma unroll
;                     for (int j = 0; j < 4; ++j) {
;                         gm1[j] = __int_as_float(__builtin_amdgcn_update_dpp(__float_as_int(p1[j]), __float_as_int(g[j]), 0x111, 0xf, 0xf, false));
;                         gm2[j] = __int_as_float(__builtin_amdgcn_update_dpp(__float_as_int(p2[j]), __float_as_int(g[j]), 0x112, 0xf, 0xf, false));
;                         if (m < 3) {
;                             p1[j] = __int_as_float(__builtin_amdgcn_update_dpp(0, __float_as_int(g[j]), 0x121, 0xf, 0xf, false));
;                             p2[j] = __int_as_float(__builtin_amdgcn_update_dpp(0, __float_as_int(g[j]), 0x122, 0xf, 0xf, false)); }
;                     }
;                     const f32x4 cv = cb[n] + w0[n] * gm2 + w1[n] * gm1 + w2[n] * g;
;                     const f32x4 up = acc[ai][1][m][n] * rs[ai][m];
;                     f32x4 y;
; #pragma unroll
;                     for (int j = 0; j < 4; ++j) y[j] = cv[j] * __builtin_amdgcn_rcpf(1.f + __builtin_amdgcn_exp2f(-cv[j] * LOG2E)) * up[j];
;                     const int tok = tok0 + 128 * ai + 16 * m;
;                     bool ok = true;
;                     if (prompt && ai == 0 && m == 0) ok = (64 * wr + fr) >= 2;
;                     if (lastT) ok = ok && tok < SEQ;
;                     if (ok) *(u32x2*)(Y + ((unsigned)tok * (unsigned)DFF + (unsigned)f)) = pk4(y);
	v_pk_mul_f32 v[110:111], v[110:111], v[200:201] op_sel_hi:[1,0]
	v_exp_f32_e32 v204, v204
	v_pk_mul_f32 v[104:105], v[104:105], v[200:201] op_sel_hi:[1,0]
	v_exp_f32_e32 v205, v205
	v_pk_mul_f32 v[106:107], v[106:107], v[200:201] op_sel_hi:[1,0]
	v_exp_f32_e32 v206, v206
	v_pk_fma_f32 v[218:219], v[128:129], v[108:109], v[136:137]
	v_exp_f32_e32 v207, v207
	v_pk_fma_f32 v[220:221], v[130:131], v[110:111], v[138:139]
	v_pk_add_f32 v[204:205], v[204:205], 1.0 op_sel_hi:[1,0]
	v_fmac_f32_dpp v218, v108, v124 row_ror:1 row_mask:0xf bank_mask:0xf
	v_pk_add_f32 v[206:207], v[206:207], 1.0 op_sel_hi:[1,0]
	v_fmac_f32_dpp v219, v109, v125 row_ror:1 row_mask:0xf bank_mask:0xf
	v_rcp_f32_e32 v204, v204
	v_fmac_f32_dpp v220, v110, v126 row_ror:1 row_mask:0xf bank_mask:0xf
	v_rcp_f32_e32 v205, v205
	v_fmac_f32_dpp v221, v111, v127 row_ror:1 row_mask:0xf bank_mask:0xf
	v_rcp_f32_e32 v206, v206
	v_fmac_f32_dpp v218, v108, v132 row_ror:2 row_mask:0xf bank_mask:0xf
	v_rcp_f32_e32 v207, v207
	v_fmac_f32_dpp v219, v109, v133 row_ror:2 row_mask:0xf bank_mask:0xf
	v_pk_mul_f32 v[222:223], v[222:223], v[204:205]
	v_fmac_f32_dpp v220, v110, v134 row_ror:2 row_mask:0xf bank_mask:0xf
	v_pk_mul_f32 v[224:225], v[224:225], v[206:207]
	v_fmac_f32_dpp v221, v111, v135 row_ror:2 row_mask:0xf bank_mask:0xf
	v_pk_mul_f32 v[112:113], v[112:113], v[222:223]
	v_fmac_f32_dpp v218, v248, v160 row_ror:12 row_mask:0xf bank_mask:0xf
	v_pk_mul_f32 v[114:115], v[114:115], v[224:225]
	v_fmac_f32_dpp v219, v249, v161 row_ror:12 row_mask:0xf bank_mask:0xf
	v_cvt_pk_bf16_f32 v112, v112, v113
	v_fmac_f32_dpp v220, v250, v162 row_ror:12 row_mask:0xf bank_mask:0xf
	v_cvt_pk_bf16_f32 v113, v114, v115
	v_fmac_f32_dpp v221, v251, v163 row_ror:12 row_mask:0xf bank_mask:0xf
	v_fmac_f32_dpp v218, v248, v164 row_ror:10 row_mask:0xf bank_mask:0xf
	v_fmac_f32_dpp v219, v249, v165 row_ror:10 row_mask:0xf bank_mask:0xf
	v_fmac_f32_dpp v220, v250, v166 row_ror:10 row_mask:0xf bank_mask:0xf
	v_fmac_f32_dpp v221, v251, v167 row_ror:10 row_mask:0xf bank_mask:0xf
	s_and_saveexec_b64 s[28:29], s[66:67]
	global_store_dwordx2 v213, v[112:113], s[46:47]
	s_mov_b64 exec, s[28:29]
	s_add_u32 s46, s46, 0x6e000
	s_addc_u32 s47, s47, 0
	v_pk_mul_f32 v[204:205], v[218:219], v[184:185] op_sel:[0,1] op_sel_hi:[1,1]
	v_pk_mul_f32 v[100:101], v[100:101], v[192:193] op_sel_hi:[1,0]
	v_pk_mul_f32 v[206:207], v[220:221], v[184:185] op_sel:[0,1] op_sel_hi:[1,1]
	v_pk_mul_f32 v[102:103], v[102:103], v[192:193] op_sel_hi:[1,0]
	v_exp_f32_e32 v204, v204
	v_pk_mul_f32 v[96:97], v[96:97], v[192:193] op_sel_hi:[1,0]
	v_exp_f32_e32 v205, v205
	v_pk_mul_f32 v[98:99], v[98:99], v[192:193] op_sel_hi:[1,0]
	v_exp_f32_e32 v206, v206
	v_pk_fma_f32 v[222:223], v[128:129], v[100:101], v[136:137]
	v_exp_f32_e32 v207, v207
	v_pk_fma_f32 v[224:225], v[130:131], v[102:103], v[138:139]
	v_pk_add_f32 v[204:205], v[204:205], 1.0 op_sel_hi:[1,0]
	v_fmac_f32_dpp v222, v100, v124 row_ror:1 row_mask:0xf bank_mask:0xf
	v_pk_add_f32 v[206:207], v[206:207], 1.0 op_sel_hi:[1,0]
	v_fmac_f32_dpp v223, v101, v125 row_ror:1 row_mask:0xf bank_mask:0xf
	v_rcp_f32_e32 v204, v204
	v_fmac_f32_dpp v224, v102, v126 row_ror:1 row_mask:0xf bank_mask:0xf
	v_rcp_f32_e32 v205, v205
	v_fmac_f32_dpp v225, v103, v127 row_ror:1 row_mask:0xf bank_mask:0xf
	v_rcp_f32_e32 v206, v206
	v_fmac_f32_dpp v222, v100, v132 row_ror:2 row_mask:0xf bank_mask:0xf
	v_rcp_f32_e32 v207, v207
	v_fmac_f32_dpp v223, v101, v133 row_ror:2 row_mask:0xf bank_mask:0xf
	v_pk_mul_f32 v[218:219], v[218:219], v[204:205]
	v_fmac_f32_dpp v224, v102, v134 row_ror:2 row_mask:0xf bank_mask:0xf
	v_pk_mul_f32 v[220:221], v[220:221], v[206:207]
	v_fmac_f32_dpp v225, v103, v135 row_ror:2 row_mask:0xf bank_mask:0xf
	v_pk_mul_f32 v[104:105], v[104:105], v[218:219]
	v_fmac_f32_dpp v222, v108, v160 row_ror:1 row_mask:0xf bank_mask:0xf
	v_pk_mul_f32 v[106:107], v[106:107], v[220:221]
	v_fmac_f32_dpp v223, v109, v161 row_ror:1 row_mask:0xf bank_mask:0xf
	v_cvt_pk_bf16_f32 v104, v104, v105
	v_fmac_f32_dpp v224, v110, v162 row_ror:1 row_mask:0xf bank_mask:0xf
	v_cvt_pk_bf16_f32 v105, v106, v107
	v_fmac_f32_dpp v225, v111, v163 row_ror:1 row_mask:0xf bank_mask:0xf
	v_fmac_f32_dpp v222, v108, v164 row_ror:2 row_mask:0xf bank_mask:0xf
	v_fmac_f32_dpp v223, v109, v165 row_ror:2 row_mask:0xf bank_mask:0xf
	v_fmac_f32_dpp v224, v110, v166 row_ror:2 row_mask:0xf bank_mask:0xf
	v_fmac_f32_dpp v225, v111, v167 row_ror:2 row_mask:0xf bank_mask:0xf
	s_and_saveexec_b64 s[28:29], s[68:69]
	global_store_dwordx2 v213, v[104:105], s[46:47]
	s_mov_b64 exec, s[28:29]
	s_add_u32 s46, s46, 0x16000
	s_addc_u32 s47, s47, 0
	v_pk_mul_f32 v[204:205], v[222:223], v[184:185] op_sel:[0,1] op_sel_hi:[1,1]
	v_pk_mul_f32 v[92:93], v[92:93], v[190:191] op_sel_hi:[1,0]
	v_pk_mul_f32 v[206:207], v[224:225], v[184:185] op_sel:[0,1] op_sel_hi:[1,1]
	v_pk_mul_f32 v[94:95], v[94:95], v[190:191] op_sel_hi:[1,0]
	v_exp_f32_e32 v204, v204
	v_pk_mul_f32 v[88:89], v[88:89], v[190:191] op_sel_hi:[1,0]
	v_exp_f32_e32 v205, v205
	v_pk_mul_f32 v[90:91], v[90:91], v[190:191] op_sel_hi:[1,0]
	v_exp_f32_e32 v206, v206
	v_pk_fma_f32 v[218:219], v[128:129], v[92:93], v[136:137]
	v_exp_f32_e32 v207, v207
	v_pk_fma_f32 v[220:221], v[130:131], v[94:95], v[138:139]
	v_pk_add_f32 v[204:205], v[204:205], 1.0 op_sel_hi:[1,0]
	v_fmac_f32_dpp v218, v92, v124 row_ror:1 row_mask:0xf bank_mask:0xf
	v_pk_add_f32 v[206:207], v[206:207], 1.0 op_sel_hi:[1,0]
	v_fmac_f32_dpp v219, v93, v125 row_ror:1 row_mask:0xf bank_mask:0xf
	v_rcp_f32_e32 v204, v204
	v_fmac_f32_dpp v220, v94, v126 row_ror:1 row_mask:0xf bank_mask:0xf
	v_rcp_f32_e32 v205, v205
; #define LAS __attribute__((address_space(3)))
;     DI void operator()(const AccT& acc, const Unit& u, int wr, int wc, int fr, int fq, LAS unsigned char* ldsx) const {
;     ...
;         for (int n = 0; n < 2; ++n) {
;             const int f = u.pn * 128 + wc * 32 + 16 * n + 4 * fq;
; #pragma unroll
;             for (int ai = 0; ai < 2; ++ai) {
;                 f32x4 hm1 = {0.f, 0.f, 0.f, 0.f}, hm2 = {0.f, 0.f, 0.f, 0.f};
;                 const int sb = 4 * (T - GU_PT) + 2 * ai + wr;
;                 if (prompt) {
;                     if (ai | wr) { const int sai = wr ? ai : ai - 1, swr = wr ^ 1; const LAS float* hp = H + ((sai * 2 + swr) * 4 + wc) * 64 + 16 * n + 4 * fq;
;                         hm2 = *(const LAS f32x4*)hp; hm1 = *(const LAS f32x4*)(hp + 32); }
;                 } else { hm2 = *(const f32x4*)(state + (size_t)(sb * 2) * DFF + f); hm1 = *(const f32x4*)(state + (size_t)(sb * 2 + 1) * DFF + f); }
;                 f32x4 p1 = hm1, p2;
; #pragma unroll
;                 for (int j = 0; j < 4; ++j) p2[j] = fr == 1 ? hm1[j] : hm2[j];
; #pragma unroll
;                 for (int m = 0; m < 4; ++m) {
;                     const f32x4 g = acc[ai][0][m][n] * rs[ai][m];
;                     f32x4 gm1, gm2;
; #pragma unroll
;                     for (int j = 0; j < 4; ++j) {
;                         gm1[j] = __int_as_float(__builtin_amdgcn_update_dpp(__float_as_int(p1[j]), __float_as_int(g[j]), 0x111, 0xf, 0xf, false));
;                         gm2[j] = __int_as_float(__builtin_amdgcn_update_dpp(__float_as_int(p2[j]), __float_as_int(g[j]), 0x112, 0xf, 0xf, false));
;                         if (m < 3) {
;                             p1[j] = __int_as_float(__builtin_amdgcn_update_dpp(0, __float_as_int(g[j]), 0x121, 0xf, 0xf, false));
;                             p2[j] = __int_as_float(__builtin_amdgcn_update_dpp(0, __float_as_int(g[j]), 0x122, 0xf, 0xf, false)); }
;                     }
;                     const f32x4 cv = cb[n] + w0[n] * gm2 + w1[n] * gm1 + w2[n] * g;
;                     const f32x4 up = acc[ai][1][m][n] * rs[ai][m];
;                     f32x4 y;
; #pragma unroll
;                     for (int j = 0; j < 4; ++j) y[j] = cv[j] * __builtin_amdgcn_rcpf(1.f + __builtin_amdgcn_exp2f(-cv[j] * LOG2E)) * up[j];
	v_fmac_f32_dpp v221, v95, v127 row_ror:1 row_mask:0xf bank_mask:0xf
	v_rcp_f32_e32 v206, v206
	v_fmac_f32_dpp v218, v92, v132 row_ror:2 row_mask:0xf bank_mask:0xf
	v_rcp_f32_e32 v207, v207
	v_fmac_f32_dpp v219, v93, v133 row_ror:2 row_mask:0xf bank_mask:0xf
	v_pk_mul_f32 v[222:223], v[222:223], v[204:205]
	v_fmac_f32_dpp v220, v94, v134 row_ror:2 row_mask:0xf bank_mask:0xf
	v_pk_mul_f32 v[224:225], v[224:225], v[206:207]
	v_fmac_f32_dpp v221, v95, v135 row_ror:2 row_mask:0xf bank_mask:0xf
	v_pk_mul_f32 v[96:97], v[96:97], v[222:223]
	v_fmac_f32_dpp v218, v100, v160 row_ror:1 row_mask:0xf bank_mask:0xf
	v_pk_mul_f32 v[98:99], v[98:99], v[224:225]
	v_fmac_f32_dpp v219, v101, v161 row_ror:1 row_mask:0xf bank_mask:0xf
	v_cvt_pk_bf16_f32 v96, v96, v97
	v_fmac_f32_dpp v220, v102, v162 row_ror:1 row_mask:0xf bank_mask:0xf
	v_cvt_pk_bf16_f32 v97, v98, v99
	v_fmac_f32_dpp v221, v103, v163 row_ror:1 row_mask:0xf bank_mask:0xf
	v_fmac_f32_dpp v218, v100, v164 row_ror:2 row_mask:0xf bank_mask:0xf
	v_fmac_f32_dpp v219, v101, v165 row_ror:2 row_mask:0xf bank_mask:0xf
	v_fmac_f32_dpp v220, v102, v166 row_ror:2 row_mask:0xf bank_mask:0xf
	v_fmac_f32_dpp v221, v103, v167 row_ror:2 row_mask:0xf bank_mask:0xf
	s_and_saveexec_b64 s[28:29], s[70:71]
	global_store_dwordx2 v213, v[96:97], s[46:47]
	s_mov_b64 exec, s[28:29]
	s_add_u32 s46, s46, 0x16000
	s_addc_u32 s47, s47, 0
	v_pk_mul_f32 v[204:205], v[218:219], v[184:185] op_sel:[0,1] op_sel_hi:[1,1]
	v_pk_mul_f32 v[84:85], v[84:85], v[184:185] op_sel_hi:[1,0]
	v_pk_mul_f32 v[206:207], v[220:221], v[184:185] op_sel:[0,1] op_sel_hi:[1,1]
	v_pk_mul_f32 v[86:87], v[86:87], v[184:185] op_sel_hi:[1,0]
	v_exp_f32_e32 v204, v204
	v_pk_mul_f32 v[80:81], v[80:81], v[184:185] op_sel_hi:[1,0]
	v_exp_f32_e32 v205, v205
	v_pk_mul_f32 v[82:83], v[82:83], v[184:185] op_sel_hi:[1,0]
	v_exp_f32_e32 v206, v206
	v_pk_fma_f32 v[222:223], v[128:129], v[84:85], v[136:137]
	v_exp_f32_e32 v207, v207
	v_pk_fma_f32 v[224:225], v[130:131], v[86:87], v[138:139]
	v_pk_add_f32 v[204:205], v[204:205], 1.0 op_sel_hi:[1,0]
	v_fmac_f32_dpp v222, v84, v124 row_ror:1 row_mask:0xf bank_mask:0xf
	v_pk_add_f32 v[206:207], v[206:207], 1.0 op_sel_hi:[1,0]
	v_fmac_f32_dpp v223, v85, v125 row_ror:1 row_mask:0xf bank_mask:0xf
	v_rcp_f32_e32 v204, v204
	v_fmac_f32_dpp v224, v86, v126 row_ror:1 row_mask:0xf bank_mask:0xf
	v_rcp_f32_e32 v205, v205
	v_fmac_f32_dpp v225, v87, v127 row_ror:1 row_mask:0xf bank_mask:0xf
	v_rcp_f32_e32 v206, v206
	v_fmac_f32_dpp v222, v84, v132 row_ror:2 row_mask:0xf bank_mask:0xf
	v_rcp_f32_e32 v207, v207
	v_fmac_f32_dpp v223, v85, v133 row_ror:2 row_mask:0xf bank_mask:0xf
	v_pk_mul_f32 v[218:219], v[218:219], v[204:205]
	v_fmac_f32_dpp v224, v86, v134 row_ror:2 row_mask:0xf bank_mask:0xf
	v_pk_mul_f32 v[220:221], v[220:221], v[206:207]
	v_fmac_f32_dpp v225, v87, v135 row_ror:2 row_mask:0xf bank_mask:0xf
	v_pk_mul_f32 v[88:89], v[88:89], v[218:219]
	v_fmac_f32_dpp v222, v92, v160 row_ror:1 row_mask:0xf bank_mask:0xf
	v_pk_mul_f32 v[90:91], v[90:91], v[220:221]
	v_fmac_f32_dpp v223, v93, v161 row_ror:1 row_mask:0xf bank_mask:0xf
	v_cvt_pk_bf16_f32 v88, v88, v89
	v_fmac_f32_dpp v224, v94, v162 row_ror:1 row_mask:0xf bank_mask:0xf
	v_cvt_pk_bf16_f32 v89, v90, v91
	v_fmac_f32_dpp v225, v95, v163 row_ror:1 row_mask:0xf bank_mask:0xf
	v_fmac_f32_dpp v222, v92, v164 row_ror:2 row_mask:0xf bank_mask:0xf
	v_fmac_f32_dpp v223, v93, v165 row_ror:2 row_mask:0xf bank_mask:0xf
	v_fmac_f32_dpp v224, v94, v166 row_ror:2 row_mask:0xf bank_mask:0xf
	v_fmac_f32_dpp v225, v95, v167 row_ror:2 row_mask:0xf bank_mask:0xf
	s_and_saveexec_b64 s[28:29], s[72:73]
	global_store_dwordx2 v213, v[88:89], s[46:47]
	s_mov_b64 exec, s[28:29]
	s_add_u32 s46, s46, 0x16000
	s_addc_u32 s47, s47, 0
	v_cndmask_b32_e64 v160, 0, v48, s[94:95]
	v_cndmask_b32_e64 v48, v48, 0, s[94:95]
	v_cndmask_b32_e64 v164, 0, v44, s[96:97]
	v_cndmask_b32_e64 v44, v44, 0, s[96:97]
	v_cndmask_b32_e64 v161, 0, v49, s[94:95]
	v_cndmask_b32_e64 v49, v49, 0, s[94:95]
	v_cndmask_b32_e64 v165, 0, v45, s[96:97]
	v_cndmask_b32_e64 v45, v45, 0, s[96:97]
	v_cndmask_b32_e64 v162, 0, v50, s[94:95]
	v_cndmask_b32_e64 v50, v50, 0, s[94:95]
	v_cndmask_b32_e64 v166, 0, v46, s[96:97]
	v_cndmask_b32_e64 v46, v46, 0, s[96:97]
	v_cndmask_b32_e64 v163, 0, v51, s[94:95]
	v_cndmask_b32_e64 v51, v51, 0, s[94:95]
	v_cndmask_b32_e64 v167, 0, v47, s[96:97]
	v_cndmask_b32_e64 v47, v47, 0, s[96:97]
	v_pk_mul_f32 v[204:205], v[222:223], v[184:185] op_sel:[0,1] op_sel_hi:[1,1]
	v_pk_mul_f32 v[76:77], v[76:77], v[214:215] op_sel_hi:[1,0]
	v_pk_mul_f32 v[206:207], v[224:225], v[184:185] op_sel:[0,1] op_sel_hi:[1,1]
	v_pk_mul_f32 v[78:79], v[78:79], v[214:215] op_sel_hi:[1,0]
	v_exp_f32_e32 v204, v204
	v_pk_mul_f32 v[72:73], v[72:73], v[214:215] op_sel_hi:[1,0]
	v_exp_f32_e32 v205, v205
	v_pk_mul_f32 v[74:75], v[74:75], v[214:215] op_sel_hi:[1,0]
	v_exp_f32_e32 v206, v206
	v_pk_fma_f32 v[218:219], v[52:53], v[76:77], v[56:57]
	v_exp_f32_e32 v207, v207
	v_pk_fma_f32 v[220:221], v[54:55], v[78:79], v[58:59]
	v_pk_add_f32 v[204:205], v[204:205], 1.0 op_sel_hi:[1,0]
	v_fmac_f32_dpp v218, v76, v48 row_ror:1 row_mask:0xf bank_mask:0xf
	v_pk_add_f32 v[206:207], v[206:207], 1.0 op_sel_hi:[1,0]
	v_fmac_f32_dpp v219, v77, v49 row_ror:1 row_mask:0xf bank_mask:0xf
	v_rcp_f32_e32 v204, v204
	v_fmac_f32_dpp v220, v78, v50 row_ror:1 row_mask:0xf bank_mask:0xf
	v_rcp_f32_e32 v205, v205
	v_fmac_f32_dpp v221, v79, v51 row_ror:1 row_mask:0xf bank_mask:0xf
	v_rcp_f32_e32 v206, v206
	v_fmac_f32_dpp v218, v76, v44 row_ror:2 row_mask:0xf bank_mask:0xf
	v_rcp_f32_e32 v207, v207
	v_fmac_f32_dpp v219, v77, v45 row_ror:2 row_mask:0xf bank_mask:0xf
; DI u32x2 pk4(f32x4 v) { u32x2 r; r.x = pk2(v[0], v[1]); r.y = pk2(v[2], v[3]); return r; }
;     DI void operator()(const AccT& acc, const Unit& u, int wr, int wc, int fr, int fq, LAS unsigned char* ldsx) const {
;     ...
;                 for (int m = 0; m < 4; ++m) {
;                     const f32x4 g = acc[ai][0][m][n] * rs[ai][m];
;                     f32x4 gm1, gm2;
; #pragma unroll
;                     for (int j = 0; j < 4; ++j) {
;                         gm1[j] = __int_as_float(__builtin_amdgcn_update_dpp(__float_as_int(p1[j]), __float_as_int(g[j]), 0x111, 0xf, 0xf, false));
;                         gm2[j] = __int_as_float(__builtin_amdgcn_update_dpp(__float_as_int(p2[j]), __float_as_int(g[j]), 0x112, 0xf, 0xf, false));
;                         if (m < 3) {
;                             p1[j] = __int_as_float(__builtin_amdgcn_update_dpp(0, __float_as_int(g[j]), 0x121, 0xf, 0xf, false));
;                             p2[j] = __int_as_float(__builtin_amdgcn_update_dpp(0, __float_as_int(g[j]), 0x122, 0xf, 0xf, false)); }
;                     }
;                     const f32x4 cv = cb[n] + w0[n] * gm2 + w1[n] * gm1 + w2[n] * g;
;                     const f32x4 up = acc[ai][1][m][n] * rs[ai][m];
;                     f32x4 y;
; #pragma unroll
;                     for (int j = 0; j < 4; ++j) y[j] = cv[j] * __builtin_amdgcn_rcpf(1.f + __builtin_amdgcn_exp2f(-cv[j] * LOG2E)) * up[j];
;                     const int tok = tok0 + 128 * ai + 16 * m;
;                     bool ok = true;
;                     if (prompt && ai == 0 && m == 0) ok = (64 * wr + fr) >= 2;
;                     if (lastT) ok = ok && tok < SEQ;
;                     if (ok) *(u32x2*)(Y + ((unsigned)tok * (unsigned)DFF + (unsigned)f)) = pk4(y);
	v_pk_mul_f32 v[222:223], v[222:223], v[204:205]
	v_fmac_f32_dpp v220, v78, v46 row_ror:2 row_mask:0xf bank_mask:0xf
	v_pk_mul_f32 v[224:225], v[224:225], v[206:207]
	v_fmac_f32_dpp v221, v79, v47 row_ror:2 row_mask:0xf bank_mask:0xf
	v_pk_mul_f32 v[80:81], v[80:81], v[222:223]
	v_fmac_f32_dpp v218, v248, v160 row_ror:8 row_mask:0xf bank_mask:0xf
	v_pk_mul_f32 v[82:83], v[82:83], v[224:225]
	v_fmac_f32_dpp v219, v249, v161 row_ror:8 row_mask:0xf bank_mask:0xf
	v_cvt_pk_bf16_f32 v80, v80, v81
	v_fmac_f32_dpp v220, v250, v162 row_ror:8 row_mask:0xf bank_mask:0xf
	v_cvt_pk_bf16_f32 v81, v82, v83
	v_fmac_f32_dpp v221, v251, v163 row_ror:8 row_mask:0xf bank_mask:0xf
	v_fmac_f32_dpp v218, v248, v164 row_ror:6 row_mask:0xf bank_mask:0xf
	v_fmac_f32_dpp v219, v249, v165 row_ror:6 row_mask:0xf bank_mask:0xf
	v_fmac_f32_dpp v220, v250, v166 row_ror:6 row_mask:0xf bank_mask:0xf
	v_fmac_f32_dpp v221, v251, v167 row_ror:6 row_mask:0xf bank_mask:0xf
	s_and_saveexec_b64 s[28:29], s[74:75]
	global_store_dwordx2 v213, v[80:81], s[46:47]
	s_mov_b64 exec, s[28:29]
	s_add_u32 s46, s54, 0xfffea000
	s_addc_u32 s47, s55, -1
	v_pk_mul_f32 v[204:205], v[218:219], v[184:185] op_sel:[0,1] op_sel_hi:[1,1]
	v_pk_mul_f32 v[68:69], v[68:69], v[210:211] op_sel_hi:[1,0]
	v_pk_mul_f32 v[206:207], v[220:221], v[184:185] op_sel:[0,1] op_sel_hi:[1,1]
	v_pk_mul_f32 v[70:71], v[70:71], v[210:211] op_sel_hi:[1,0]
	v_exp_f32_e32 v204, v204
	v_pk_mul_f32 v[64:65], v[64:65], v[210:211] op_sel_hi:[1,0]
	v_exp_f32_e32 v205, v205
	v_pk_mul_f32 v[66:67], v[66:67], v[210:211] op_sel_hi:[1,0]
	v_exp_f32_e32 v206, v206
	v_pk_fma_f32 v[222:223], v[52:53], v[68:69], v[56:57]
	v_exp_f32_e32 v207, v207
	v_pk_fma_f32 v[224:225], v[54:55], v[70:71], v[58:59]
	v_pk_add_f32 v[204:205], v[204:205], 1.0 op_sel_hi:[1,0]
	v_fmac_f32_dpp v222, v68, v48 row_ror:1 row_mask:0xf bank_mask:0xf
	v_pk_add_f32 v[206:207], v[206:207], 1.0 op_sel_hi:[1,0]
	v_fmac_f32_dpp v223, v69, v49 row_ror:1 row_mask:0xf bank_mask:0xf
	v_rcp_f32_e32 v204, v204
	v_fmac_f32_dpp v224, v70, v50 row_ror:1 row_mask:0xf bank_mask:0xf
	v_rcp_f32_e32 v205, v205
	v_fmac_f32_dpp v225, v71, v51 row_ror:1 row_mask:0xf bank_mask:0xf
	v_rcp_f32_e32 v206, v206
	v_fmac_f32_dpp v222, v68, v44 row_ror:2 row_mask:0xf bank_mask:0xf
	v_rcp_f32_e32 v207, v207
	v_fmac_f32_dpp v223, v69, v45 row_ror:2 row_mask:0xf bank_mask:0xf
	v_pk_mul_f32 v[218:219], v[218:219], v[204:205]
	v_fmac_f32_dpp v224, v70, v46 row_ror:2 row_mask:0xf bank_mask:0xf
	v_pk_mul_f32 v[220:221], v[220:221], v[206:207]
	v_fmac_f32_dpp v225, v71, v47 row_ror:2 row_mask:0xf bank_mask:0xf
	v_pk_mul_f32 v[72:73], v[72:73], v[218:219]
	v_fmac_f32_dpp v222, v76, v160 row_ror:1 row_mask:0xf bank_mask:0xf
	v_pk_mul_f32 v[74:75], v[74:75], v[220:221]
	v_fmac_f32_dpp v223, v77, v161 row_ror:1 row_mask:0xf bank_mask:0xf
	v_cvt_pk_bf16_f32 v72, v72, v73
	v_fmac_f32_dpp v224, v78, v162 row_ror:1 row_mask:0xf bank_mask:0xf
	v_cvt_pk_bf16_f32 v73, v74, v75
	v_fmac_f32_dpp v225, v79, v163 row_ror:1 row_mask:0xf bank_mask:0xf
	v_fmac_f32_dpp v222, v76, v164 row_ror:2 row_mask:0xf bank_mask:0xf
	v_fmac_f32_dpp v223, v77, v165 row_ror:2 row_mask:0xf bank_mask:0xf
	v_fmac_f32_dpp v224, v78, v166 row_ror:2 row_mask:0xf bank_mask:0xf
	v_fmac_f32_dpp v225, v79, v167 row_ror:2 row_mask:0xf bank_mask:0xf
	s_and_saveexec_b64 s[28:29], s[60:61]
	global_store_dwordx2 v213, v[72:73], s[46:47] offset:32
	s_mov_b64 exec, s[28:29]
	s_add_u32 s46, s46, 0x16000
	s_addc_u32 s47, s47, 0
	v_pk_mul_f32 v[204:205], v[222:223], v[184:185] op_sel:[0,1] op_sel_hi:[1,1]
	v_pk_mul_f32 v[60:61], v[60:61], v[208:209] op_sel_hi:[1,0]
	v_pk_mul_f32 v[206:207], v[224:225], v[184:185] op_sel:[0,1] op_sel_hi:[1,1]
	v_pk_mul_f32 v[62:63], v[62:63], v[208:209] op_sel_hi:[1,0]
	v_exp_f32_e32 v204, v204
	v_pk_mul_f32 v[40:41], v[40:41], v[208:209] op_sel_hi:[1,0]
	v_exp_f32_e32 v205, v205
	v_pk_mul_f32 v[42:43], v[42:43], v[208:209] op_sel_hi:[1,0]
	v_exp_f32_e32 v206, v206
	v_pk_fma_f32 v[218:219], v[52:53], v[60:61], v[56:57]
	v_exp_f32_e32 v207, v207
	v_pk_fma_f32 v[220:221], v[54:55], v[62:63], v[58:59]
	v_pk_add_f32 v[204:205], v[204:205], 1.0 op_sel_hi:[1,0]
	v_fmac_f32_dpp v218, v60, v48 row_ror:1 row_mask:0xf bank_mask:0xf
	v_pk_add_f32 v[206:207], v[206:207], 1.0 op_sel_hi:[1,0]
	v_fmac_f32_dpp v219, v61, v49 row_ror:1 row_mask:0xf bank_mask:0xf
	v_rcp_f32_e32 v204, v204
	v_fmac_f32_dpp v220, v62, v50 row_ror:1 row_mask:0xf bank_mask:0xf
	v_rcp_f32_e32 v205, v205
	v_fmac_f32_dpp v221, v63, v51 row_ror:1 row_mask:0xf bank_mask:0xf
	v_rcp_f32_e32 v206, v206
	v_fmac_f32_dpp v218, v60, v44 row_ror:2 row_mask:0xf bank_mask:0xf
	v_rcp_f32_e32 v207, v207
	v_fmac_f32_dpp v219, v61, v45 row_ror:2 row_mask:0xf bank_mask:0xf
	v_pk_mul_f32 v[222:223], v[222:223], v[204:205]
	v_fmac_f32_dpp v220, v62, v46 row_ror:2 row_mask:0xf bank_mask:0xf
	v_pk_mul_f32 v[224:225], v[224:225], v[206:207]
	v_fmac_f32_dpp v221, v63, v47 row_ror:2 row_mask:0xf bank_mask:0xf
	v_pk_mul_f32 v[64:65], v[64:65], v[222:223]
	v_fmac_f32_dpp v218, v68, v160 row_ror:1 row_mask:0xf bank_mask:0xf
	v_pk_mul_f32 v[66:67], v[66:67], v[224:225]
	v_fmac_f32_dpp v219, v69, v161 row_ror:1 row_mask:0xf bank_mask:0xf
	v_cvt_pk_bf16_f32 v64, v64, v65
	v_fmac_f32_dpp v220, v70, v162 row_ror:1 row_mask:0xf bank_mask:0xf
	v_cvt_pk_bf16_f32 v65, v66, v67
	v_fmac_f32_dpp v221, v71, v163 row_ror:1 row_mask:0xf bank_mask:0xf
	v_fmac_f32_dpp v218, v68, v164 row_ror:2 row_mask:0xf bank_mask:0xf
	v_fmac_f32_dpp v219, v69, v165 row_ror:2 row_mask:0xf bank_mask:0xf
	v_fmac_f32_dpp v220, v70, v166 row_ror:2 row_mask:0xf bank_mask:0xf
	v_fmac_f32_dpp v221, v71, v167 row_ror:2 row_mask:0xf bank_mask:0xf
; DI u32x2 pk4(f32x4 v) { u32x2 r; r.x = pk2(v[0], v[1]); r.y = pk2(v[2], v[3]); return r; }
;     DI void operator()(const AccT& acc, const Unit& u, int wr, int wc, int fr, int fq, LAS unsigned char* ldsx) const {
;     ...
;                 for (int m = 0; m < 4; ++m) {
;                     const f32x4 g = acc[ai][0][m][n] * rs[ai][m];
;                     f32x4 gm1, gm2;
; #pragma unroll
;                     for (int j = 0; j < 4; ++j) {
;                         gm1[j] = __int_as_float(__builtin_amdgcn_update_dpp(__float_as_int(p1[j]), __float_as_int(g[j]), 0x111, 0xf, 0xf, false));
;                         gm2[j] = __int_as_float(__builtin_amdgcn_update_dpp(__float_as_int(p2[j]), __float_as_int(g[j]), 0x112, 0xf, 0xf, false));
;                         if (m < 3) {
;                             p1[j] = __int_as_float(__builtin_amdgcn_update_dpp(0, __float_as_int(g[j]), 0x121, 0xf, 0xf, false));
;                             p2[j] = __int_as_float(__builtin_amdgcn_update_dpp(0, __float_as_int(g[j]), 0x122, 0xf, 0xf, false)); }
;                     }
;                     const f32x4 cv = cb[n] + w0[n] * gm2 + w1[n] * gm1 + w2[n] * g;
;                     const f32x4 up = acc[ai][1][m][n] * rs[ai][m];
;                     f32x4 y;
; #pragma unroll
;                     for (int j = 0; j < 4; ++j) y[j] = cv[j] * __builtin_amdgcn_rcpf(1.f + __builtin_amdgcn_exp2f(-cv[j] * LOG2E)) * up[j];
;                     const int tok = tok0 + 128 * ai + 16 * m;
;                     bool ok = true;
;                     if (prompt && ai == 0 && m == 0) ok = (64 * wr + fr) >= 2;
;                     if (lastT) ok = ok && tok < SEQ;
;                     if (ok) *(u32x2*)(Y + ((unsigned)tok * (unsigned)DFF + (unsigned)f)) = pk4(y);
	s_and_saveexec_b64 s[28:29], s[62:63]
	global_store_dwordx2 v213, v[64:65], s[46:47] offset:32
	s_mov_b64 exec, s[28:29]
	s_add_u32 s46, s46, 0x16000
	s_addc_u32 s47, s47, 0
	v_pk_mul_f32 v[204:205], v[218:219], v[184:185] op_sel:[0,1] op_sel_hi:[1,1]
	v_pk_mul_f32 v[36:37], v[36:37], v[202:203] op_sel_hi:[1,0]
	v_pk_mul_f32 v[206:207], v[220:221], v[184:185] op_sel:[0,1] op_sel_hi:[1,1]
	v_pk_mul_f32 v[38:39], v[38:39], v[202:203] op_sel_hi:[1,0]
	v_exp_f32_e32 v204, v204
	v_pk_mul_f32 v[32:33], v[32:33], v[202:203] op_sel_hi:[1,0]
	v_exp_f32_e32 v205, v205
	v_pk_mul_f32 v[34:35], v[34:35], v[202:203] op_sel_hi:[1,0]
	v_exp_f32_e32 v206, v206
	v_pk_fma_f32 v[222:223], v[52:53], v[36:37], v[56:57]
	v_exp_f32_e32 v207, v207
	v_pk_fma_f32 v[224:225], v[54:55], v[38:39], v[58:59]
	v_pk_add_f32 v[204:205], v[204:205], 1.0 op_sel_hi:[1,0]
	v_fmac_f32_dpp v222, v36, v48 row_ror:1 row_mask:0xf bank_mask:0xf
	v_pk_add_f32 v[206:207], v[206:207], 1.0 op_sel_hi:[1,0]
	v_fmac_f32_dpp v223, v37, v49 row_ror:1 row_mask:0xf bank_mask:0xf
	v_rcp_f32_e32 v204, v204
	v_fmac_f32_dpp v224, v38, v50 row_ror:1 row_mask:0xf bank_mask:0xf
	v_rcp_f32_e32 v205, v205
	v_fmac_f32_dpp v225, v39, v51 row_ror:1 row_mask:0xf bank_mask:0xf
	v_rcp_f32_e32 v206, v206
	v_fmac_f32_dpp v222, v36, v44 row_ror:2 row_mask:0xf bank_mask:0xf
	v_rcp_f32_e32 v207, v207
	v_fmac_f32_dpp v223, v37, v45 row_ror:2 row_mask:0xf bank_mask:0xf
	v_pk_mul_f32 v[218:219], v[218:219], v[204:205]
	v_fmac_f32_dpp v224, v38, v46 row_ror:2 row_mask:0xf bank_mask:0xf
	v_pk_mul_f32 v[220:221], v[220:221], v[206:207]
	v_fmac_f32_dpp v225, v39, v47 row_ror:2 row_mask:0xf bank_mask:0xf
	v_pk_mul_f32 v[40:41], v[40:41], v[218:219]
	v_fmac_f32_dpp v222, v60, v160 row_ror:1 row_mask:0xf bank_mask:0xf
	v_pk_mul_f32 v[42:43], v[42:43], v[220:221]
	v_fmac_f32_dpp v223, v61, v161 row_ror:1 row_mask:0xf bank_mask:0xf
	v_cvt_pk_bf16_f32 v40, v40, v41
	v_fmac_f32_dpp v224, v62, v162 row_ror:1 row_mask:0xf bank_mask:0xf
	v_cvt_pk_bf16_f32 v41, v42, v43
	v_fmac_f32_dpp v225, v63, v163 row_ror:1 row_mask:0xf bank_mask:0xf
	v_fmac_f32_dpp v222, v60, v164 row_ror:2 row_mask:0xf bank_mask:0xf
	v_fmac_f32_dpp v223, v61, v165 row_ror:2 row_mask:0xf bank_mask:0xf
	v_fmac_f32_dpp v224, v62, v166 row_ror:2 row_mask:0xf bank_mask:0xf
	v_fmac_f32_dpp v225, v63, v167 row_ror:2 row_mask:0xf bank_mask:0xf
	s_and_saveexec_b64 s[28:29], s[64:65]
	global_store_dwordx2 v213, v[40:41], s[46:47] offset:32
	s_mov_b64 exec, s[28:29]
	s_add_u32 s46, s46, 0x16000
	s_addc_u32 s47, s47, 0
	v_pk_mul_f32 v[204:205], v[222:223], v[184:185] op_sel:[0,1] op_sel_hi:[1,1]
	v_pk_mul_f32 v[28:29], v[28:29], v[200:201] op_sel_hi:[1,0]
	v_pk_mul_f32 v[206:207], v[224:225], v[184:185] op_sel:[0,1] op_sel_hi:[1,1]
	v_pk_mul_f32 v[30:31], v[30:31], v[200:201] op_sel_hi:[1,0]
	v_exp_f32_e32 v204, v204
	v_pk_mul_f32 v[24:25], v[24:25], v[200:201] op_sel_hi:[1,0]
	v_exp_f32_e32 v205, v205
	v_pk_mul_f32 v[26:27], v[26:27], v[200:201] op_sel_hi:[1,0]
	v_exp_f32_e32 v206, v206
	v_pk_fma_f32 v[218:219], v[52:53], v[28:29], v[56:57]
	v_exp_f32_e32 v207, v207
	v_pk_fma_f32 v[220:221], v[54:55], v[30:31], v[58:59]
	v_pk_add_f32 v[204:205], v[204:205], 1.0 op_sel_hi:[1,0]
	v_fmac_f32_dpp v218, v28, v48 row_ror:1 row_mask:0xf bank_mask:0xf
	v_pk_add_f32 v[206:207], v[206:207], 1.0 op_sel_hi:[1,0]
	v_fmac_f32_dpp v219, v29, v49 row_ror:1 row_mask:0xf bank_mask:0xf
	v_rcp_f32_e32 v204, v204
	v_fmac_f32_dpp v220, v30, v50 row_ror:1 row_mask:0xf bank_mask:0xf
	v_rcp_f32_e32 v205, v205
	v_fmac_f32_dpp v221, v31, v51 row_ror:1 row_mask:0xf bank_mask:0xf
	v_rcp_f32_e32 v206, v206
	v_fmac_f32_dpp v218, v28, v44 row_ror:2 row_mask:0xf bank_mask:0xf
	v_rcp_f32_e32 v207, v207
	v_fmac_f32_dpp v219, v29, v45 row_ror:2 row_mask:0xf bank_mask:0xf
	v_pk_mul_f32 v[222:223], v[222:223], v[204:205]
	v_fmac_f32_dpp v220, v30, v46 row_ror:2 row_mask:0xf bank_mask:0xf
	v_pk_mul_f32 v[224:225], v[224:225], v[206:207]
	v_fmac_f32_dpp v221, v31, v47 row_ror:2 row_mask:0xf bank_mask:0xf
	v_pk_mul_f32 v[32:33], v[32:33], v[222:223]
	v_fmac_f32_dpp v218, v248, v160 row_ror:4 row_mask:0xf bank_mask:0xf
	v_pk_mul_f32 v[34:35], v[34:35], v[224:225]
	v_fmac_f32_dpp v219, v249, v161 row_ror:4 row_mask:0xf bank_mask:0xf
	v_cvt_pk_bf16_f32 v32, v32, v33
	v_fmac_f32_dpp v220, v250, v162 row_ror:4 row_mask:0xf bank_mask:0xf
	v_cvt_pk_bf16_f32 v33, v34, v35
	v_fmac_f32_dpp v221, v251, v163 row_ror:4 row_mask:0xf bank_mask:0xf
	v_fmac_f32_dpp v218, v248, v164 row_ror:2 row_mask:0xf bank_mask:0xf
	v_fmac_f32_dpp v219, v249, v165 row_ror:2 row_mask:0xf bank_mask:0xf
	v_fmac_f32_dpp v220, v250, v166 row_ror:2 row_mask:0xf bank_mask:0xf
	v_fmac_f32_dpp v221, v251, v167 row_ror:2 row_mask:0xf bank_mask:0xf
	s_and_saveexec_b64 s[28:29], s[66:67]
	global_store_dwordx2 v213, v[32:33], s[46:47] offset:32
	s_mov_b64 exec, s[28:29]
	s_add_u32 s46, s46, 0x6e000
	s_addc_u32 s47, s47, 0
	v_pk_mul_f32 v[204:205], v[218:219], v[184:185] op_sel:[0,1] op_sel_hi:[1,1]
	v_pk_mul_f32 v[20:21], v[20:21], v[192:193] op_sel_hi:[1,0]
	v_pk_mul_f32 v[206:207], v[220:221], v[184:185] op_sel:[0,1] op_sel_hi:[1,1]
	v_pk_mul_f32 v[22:23], v[22:23], v[192:193] op_sel_hi:[1,0]
	v_exp_f32_e32 v204, v204
	v_pk_mul_f32 v[16:17], v[16:17], v[192:193] op_sel_hi:[1,0]
	v_exp_f32_e32 v205, v205
	v_pk_mul_f32 v[18:19], v[18:19], v[192:193] op_sel_hi:[1,0]
	v_exp_f32_e32 v206, v206
	v_pk_fma_f32 v[222:223], v[52:53], v[20:21], v[56:57]
	v_exp_f32_e32 v207, v207
	v_pk_fma_f32 v[224:225], v[54:55], v[22:23], v[58:59]
	v_pk_add_f32 v[204:205], v[204:205], 1.0 op_sel_hi:[1,0]
	v_fmac_f32_dpp v222, v20, v48 row_ror:1 row_mask:0xf bank_mask:0xf
; DI u32x2 pk4(f32x4 v) { u32x2 r; r.x = pk2(v[0], v[1]); r.y = pk2(v[2], v[3]); return r; }
;     DI void operator()(const AccT& acc, const Unit& u, int wr, int wc, int fr, int fq, LAS unsigned char* ldsx) const {
;     ...
;                 for (int m = 0; m < 4; ++m) {
;                     const f32x4 g = acc[ai][0][m][n] * rs[ai][m];
;                     f32x4 gm1, gm2;
; #pragma unroll
;                     for (int j = 0; j < 4; ++j) {
;                         gm1[j] = __int_as_float(__builtin_amdgcn_update_dpp(__float_as_int(p1[j]), __float_as_int(g[j]), 0x111, 0xf, 0xf, false));
;                         gm2[j] = __int_as_float(__builtin_amdgcn_update_dpp(__float_as_int(p2[j]), __float_as_int(g[j]), 0x112, 0xf, 0xf, false));
;                         if (m < 3) {
;                             p1[j] = __int_as_float(__builtin_amdgcn_update_dpp(0, __float_as_int(g[j]), 0x121, 0xf, 0xf, false));
;                             p2[j] = __int_as_float(__builtin_amdgcn_update_dpp(0, __float_as_int(g[j]), 0x122, 0xf, 0xf, false)); }
;                     }
;                     const f32x4 cv = cb[n] + w0[n] * gm2 + w1[n] * gm1 + w2[n] * g;
;                     const f32x4 up = acc[ai][1][m][n] * rs[ai][m];
;                     f32x4 y;
; #pragma unroll
;                     for (int j = 0; j < 4; ++j) y[j] = cv[j] * __builtin_amdgcn_rcpf(1.f + __builtin_amdgcn_exp2f(-cv[j] * LOG2E)) * up[j];
;                     const int tok = tok0 + 128 * ai + 16 * m;
;                     bool ok = true;
;                     if (prompt && ai == 0 && m == 0) ok = (64 * wr + fr) >= 2;
;                     if (lastT) ok = ok && tok < SEQ;
;                     if (ok) *(u32x2*)(Y + ((unsigned)tok * (unsigned)DFF + (unsigned)f)) = pk4(y);
	v_pk_add_f32 v[206:207], v[206:207], 1.0 op_sel_hi:[1,0]
	v_fmac_f32_dpp v223, v21, v49 row_ror:1 row_mask:0xf bank_mask:0xf
	v_rcp_f32_e32 v204, v204
	v_fmac_f32_dpp v224, v22, v50 row_ror:1 row_mask:0xf bank_mask:0xf
	v_rcp_f32_e32 v205, v205
	v_fmac_f32_dpp v225, v23, v51 row_ror:1 row_mask:0xf bank_mask:0xf
	v_rcp_f32_e32 v206, v206
	v_fmac_f32_dpp v222, v20, v44 row_ror:2 row_mask:0xf bank_mask:0xf
	v_rcp_f32_e32 v207, v207
	v_fmac_f32_dpp v223, v21, v45 row_ror:2 row_mask:0xf bank_mask:0xf
	v_pk_mul_f32 v[218:219], v[218:219], v[204:205]
	v_fmac_f32_dpp v224, v22, v46 row_ror:2 row_mask:0xf bank_mask:0xf
	v_pk_mul_f32 v[220:221], v[220:221], v[206:207]
	v_fmac_f32_dpp v225, v23, v47 row_ror:2 row_mask:0xf bank_mask:0xf
	v_pk_mul_f32 v[24:25], v[24:25], v[218:219]
	v_fmac_f32_dpp v222, v28, v160 row_ror:1 row_mask:0xf bank_mask:0xf
	v_pk_mul_f32 v[26:27], v[26:27], v[220:221]
	v_fmac_f32_dpp v223, v29, v161 row_ror:1 row_mask:0xf bank_mask:0xf
	v_cvt_pk_bf16_f32 v24, v24, v25
	v_fmac_f32_dpp v224, v30, v162 row_ror:1 row_mask:0xf bank_mask:0xf
	v_cvt_pk_bf16_f32 v25, v26, v27
	v_fmac_f32_dpp v225, v31, v163 row_ror:1 row_mask:0xf bank_mask:0xf
	v_fmac_f32_dpp v222, v28, v164 row_ror:2 row_mask:0xf bank_mask:0xf
	v_fmac_f32_dpp v223, v29, v165 row_ror:2 row_mask:0xf bank_mask:0xf
	v_fmac_f32_dpp v224, v30, v166 row_ror:2 row_mask:0xf bank_mask:0xf
	v_fmac_f32_dpp v225, v31, v167 row_ror:2 row_mask:0xf bank_mask:0xf
	s_and_saveexec_b64 s[28:29], s[68:69]
	global_store_dwordx2 v213, v[24:25], s[46:47] offset:32
	s_mov_b64 exec, s[28:29]
	s_add_u32 s46, s46, 0x16000
	s_addc_u32 s47, s47, 0
	v_pk_mul_f32 v[204:205], v[222:223], v[184:185] op_sel:[0,1] op_sel_hi:[1,1]
	v_pk_mul_f32 v[12:13], v[12:13], v[190:191] op_sel_hi:[1,0]
	v_pk_mul_f32 v[206:207], v[224:225], v[184:185] op_sel:[0,1] op_sel_hi:[1,1]
	v_pk_mul_f32 v[14:15], v[14:15], v[190:191] op_sel_hi:[1,0]
	v_exp_f32_e32 v204, v204
	v_pk_mul_f32 v[8:9], v[8:9], v[190:191] op_sel_hi:[1,0]
	v_exp_f32_e32 v205, v205
	v_pk_mul_f32 v[10:11], v[10:11], v[190:191] op_sel_hi:[1,0]
	v_exp_f32_e32 v206, v206
	v_pk_fma_f32 v[218:219], v[52:53], v[12:13], v[56:57]
	v_exp_f32_e32 v207, v207
	v_pk_fma_f32 v[220:221], v[54:55], v[14:15], v[58:59]
	v_pk_add_f32 v[204:205], v[204:205], 1.0 op_sel_hi:[1,0]
	v_fmac_f32_dpp v218, v12, v48 row_ror:1 row_mask:0xf bank_mask:0xf
	v_pk_add_f32 v[206:207], v[206:207], 1.0 op_sel_hi:[1,0]
	v_fmac_f32_dpp v219, v13, v49 row_ror:1 row_mask:0xf bank_mask:0xf
	v_rcp_f32_e32 v204, v204
	v_fmac_f32_dpp v220, v14, v50 row_ror:1 row_mask:0xf bank_mask:0xf
	v_rcp_f32_e32 v205, v205
	v_fmac_f32_dpp v221, v15, v51 row_ror:1 row_mask:0xf bank_mask:0xf
	v_rcp_f32_e32 v206, v206
	v_fmac_f32_dpp v218, v12, v44 row_ror:2 row_mask:0xf bank_mask:0xf
	v_rcp_f32_e32 v207, v207
	v_fmac_f32_dpp v219, v13, v45 row_ror:2 row_mask:0xf bank_mask:0xf
	v_pk_mul_f32 v[222:223], v[222:223], v[204:205]
	v_fmac_f32_dpp v220, v14, v46 row_ror:2 row_mask:0xf bank_mask:0xf
	v_pk_mul_f32 v[224:225], v[224:225], v[206:207]
	v_fmac_f32_dpp v221, v15, v47 row_ror:2 row_mask:0xf bank_mask:0xf
	v_pk_mul_f32 v[16:17], v[16:17], v[222:223]
	v_fmac_f32_dpp v218, v20, v160 row_ror:1 row_mask:0xf bank_mask:0xf
	v_pk_mul_f32 v[18:19], v[18:19], v[224:225]
	v_fmac_f32_dpp v219, v21, v161 row_ror:1 row_mask:0xf bank_mask:0xf
	v_cvt_pk_bf16_f32 v16, v16, v17
	v_fmac_f32_dpp v220, v22, v162 row_ror:1 row_mask:0xf bank_mask:0xf
	v_cvt_pk_bf16_f32 v17, v18, v19
	v_fmac_f32_dpp v221, v23, v163 row_ror:1 row_mask:0xf bank_mask:0xf
	v_fmac_f32_dpp v218, v20, v164 row_ror:2 row_mask:0xf bank_mask:0xf
	v_fmac_f32_dpp v219, v21, v165 row_ror:2 row_mask:0xf bank_mask:0xf
	v_fmac_f32_dpp v220, v22, v166 row_ror:2 row_mask:0xf bank_mask:0xf
	v_fmac_f32_dpp v221, v23, v167 row_ror:2 row_mask:0xf bank_mask:0xf
	s_and_saveexec_b64 s[28:29], s[70:71]
	global_store_dwordx2 v213, v[16:17], s[46:47] offset:32
	s_mov_b64 exec, s[28:29]
	s_add_u32 s46, s46, 0x16000
	s_addc_u32 s47, s47, 0
	v_pk_mul_f32 v[204:205], v[218:219], v[184:185] op_sel:[0,1] op_sel_hi:[1,1]
	v_pk_mul_f32 v[4:5], v[4:5], v[184:185] op_sel_hi:[1,0]
	v_pk_mul_f32 v[206:207], v[220:221], v[184:185] op_sel:[0,1] op_sel_hi:[1,1]
	v_pk_mul_f32 v[6:7], v[6:7], v[184:185] op_sel_hi:[1,0]
	v_exp_f32_e32 v204, v204
	v_pk_mul_f32 v[0:1], v[0:1], v[184:185] op_sel_hi:[1,0]
	v_exp_f32_e32 v205, v205
	v_pk_mul_f32 v[2:3], v[2:3], v[184:185] op_sel_hi:[1,0]
	v_exp_f32_e32 v206, v206
	v_pk_fma_f32 v[222:223], v[52:53], v[4:5], v[56:57]
	v_exp_f32_e32 v207, v207
	v_pk_fma_f32 v[224:225], v[54:55], v[6:7], v[58:59]
	v_pk_add_f32 v[204:205], v[204:205], 1.0 op_sel_hi:[1,0]
	v_fmac_f32_dpp v222, v4, v48 row_ror:1 row_mask:0xf bank_mask:0xf
	v_pk_add_f32 v[206:207], v[206:207], 1.0 op_sel_hi:[1,0]
	v_fmac_f32_dpp v223, v5, v49 row_ror:1 row_mask:0xf bank_mask:0xf
	v_rcp_f32_e32 v204, v204
	v_fmac_f32_dpp v224, v6, v50 row_ror:1 row_mask:0xf bank_mask:0xf
	v_rcp_f32_e32 v205, v205
	v_fmac_f32_dpp v225, v7, v51 row_ror:1 row_mask:0xf bank_mask:0xf
	v_rcp_f32_e32 v206, v206
	v_fmac_f32_dpp v222, v4, v44 row_ror:2 row_mask:0xf bank_mask:0xf
	v_rcp_f32_e32 v207, v207
	v_fmac_f32_dpp v223, v5, v45 row_ror:2 row_mask:0xf bank_mask:0xf
	v_pk_mul_f32 v[218:219], v[218:219], v[204:205]
	v_fmac_f32_dpp v224, v6, v46 row_ror:2 row_mask:0xf bank_mask:0xf
	v_pk_mul_f32 v[220:221], v[220:221], v[206:207]
	v_fmac_f32_dpp v225, v7, v47 row_ror:2 row_mask:0xf bank_mask:0xf
	v_pk_mul_f32 v[8:9], v[8:9], v[218:219]
	v_fmac_f32_dpp v222, v12, v160 row_ror:1 row_mask:0xf bank_mask:0xf
	v_pk_mul_f32 v[10:11], v[10:11], v[220:221]
	v_fmac_f32_dpp v223, v13, v161 row_ror:1 row_mask:0xf bank_mask:0xf
; DI u32x2 pk4(f32x4 v) { u32x2 r; r.x = pk2(v[0], v[1]); r.y = pk2(v[2], v[3]); return r; }
;     DI void operator()(const AccT& acc, const Unit& u, int wr, int wc, int fr, int fq, LAS unsigned char* ldsx) const {
;     ...
;                     const f32x4 cv = cb[n] + w0[n] * gm2 + w1[n] * gm1 + w2[n] * g;
;                     const f32x4 up = acc[ai][1][m][n] * rs[ai][m];
;                     f32x4 y;
; #pragma unroll
;                     for (int j = 0; j < 4; ++j) y[j] = cv[j] * __builtin_amdgcn_rcpf(1.f + __builtin_amdgcn_exp2f(-cv[j] * LOG2E)) * up[j];
;                     const int tok = tok0 + 128 * ai + 16 * m;
;                     bool ok = true;
;                     if (prompt && ai == 0 && m == 0) ok = (64 * wr + fr) >= 2;
;                     if (lastT) ok = ok && tok < SEQ;
;                     if (ok) *(u32x2*)(Y + ((unsigned)tok * (unsigned)DFF + (unsigned)f)) = pk4(y);
;                     if (lastT) { if (tok == SEQ - 2 || tok == SEQ - 1) *(f32x4*)(out + OFF_CVP + (size_t)(tok - (SEQ - 2)) * DFF + f) = g; }
;                     if (!prompt && m == 3 && fr >= 14) *(f32x4*)(out + OFF_CVS + (size_t)(sb * 2 + (fr - 14)) * DFF + f) = g;
	v_cvt_pk_bf16_f32 v8, v8, v9
	v_fmac_f32_dpp v224, v14, v162 row_ror:1 row_mask:0xf bank_mask:0xf
	v_cvt_pk_bf16_f32 v9, v10, v11
	v_fmac_f32_dpp v225, v15, v163 row_ror:1 row_mask:0xf bank_mask:0xf
	v_fmac_f32_dpp v222, v12, v164 row_ror:2 row_mask:0xf bank_mask:0xf
	v_fmac_f32_dpp v223, v13, v165 row_ror:2 row_mask:0xf bank_mask:0xf
	v_fmac_f32_dpp v224, v14, v166 row_ror:2 row_mask:0xf bank_mask:0xf
	v_fmac_f32_dpp v225, v15, v167 row_ror:2 row_mask:0xf bank_mask:0xf
	s_and_saveexec_b64 s[28:29], s[72:73]
	global_store_dwordx2 v213, v[8:9], s[46:47] offset:32
	s_mov_b64 exec, s[28:29]
	s_add_u32 s46, s46, 0x16000
	s_addc_u32 s47, s47, 0
	v_pk_mul_f32 v[204:205], v[222:223], v[184:185] op_sel:[0,1] op_sel_hi:[1,1]
	v_pk_mul_f32 v[206:207], v[224:225], v[184:185] op_sel:[0,1] op_sel_hi:[1,1]
	v_exp_f32_e32 v204, v204
	v_exp_f32_e32 v205, v205
	v_exp_f32_e32 v206, v206
	v_exp_f32_e32 v207, v207
	v_pk_add_f32 v[204:205], v[204:205], 1.0 op_sel_hi:[1,0]
	v_pk_add_f32 v[206:207], v[206:207], 1.0 op_sel_hi:[1,0]
	v_rcp_f32_e32 v204, v204
	v_rcp_f32_e32 v205, v205
	v_rcp_f32_e32 v206, v206
	v_rcp_f32_e32 v207, v207
	v_pk_mul_f32 v[222:223], v[222:223], v[204:205]
	v_pk_mul_f32 v[224:225], v[224:225], v[206:207]
	v_pk_mul_f32 v[0:1], v[0:1], v[222:223]
	v_pk_mul_f32 v[2:3], v[2:3], v[224:225]
	v_cvt_pk_bf16_f32 v0, v0, v1
	v_cvt_pk_bf16_f32 v1, v2, v3
	s_and_saveexec_b64 s[28:29], s[74:75]
	global_store_dwordx2 v213, v[0:1], s[46:47] offset:32
	s_mov_b64 exec, s[28:29]
	s_add_u32 s46, s54, 0xfffea000
	s_addc_u32 s47, s55, -1
	s_cmp_gt_i32 s42, 64
	s_cbranch_scc0 .Lgu_nocvs
	v_readlane_b32 s30, v252, 0
	v_readlane_b32 s31, v252, 1
	s_lshl_b32 s23, s42, 2
	s_add_i32 s23, s36, s23
	s_lshl_b32 s23, s23, 1
	s_movk_i32 s76, 0x2c00
	v_add_u32_e32 v186, s23, v233
	v_mad_i64_i32 v[186:187], s[34:35], v186, s76, 0
	v_lshl_add_u64 v[186:187], s[14:15], 0, v[186:187]
	v_lshl_add_u64 v[186:187], v[216:217], 2, v[186:187]
	s_and_saveexec_b64 s[28:29], s[30:31]
	global_store_dwordx4 v[186:187], v[116:119], off
	global_store_dwordx4 v[186:187], v[36:39], off offset:64
	s_mov_b64 exec, s[28:29]
	s_add_i32 s23, s23, 4
	v_add_u32_e32 v186, s23, v233
	v_mad_i64_i32 v[186:187], s[34:35], v186, s76, 0
	v_lshl_add_u64 v[186:187], s[14:15], 0, v[186:187]
	v_lshl_add_u64 v[186:187], v[216:217], 2, v[186:187]
	s_and_saveexec_b64 s[28:29], s[30:31]
	global_store_dwordx4 v[186:187], v[84:87], off
	global_store_dwordx4 v[186:187], v[4:7], off offset:64
	s_mov_b64 exec, s[28:29]
.Lgu_nocvs:
	s_cmp_eq_u32 s42, 64
	s_cbranch_scc0 .Lgu_nocvp
	v_mov_b32_e32 v186, v172
	v_and_b32_e32 v187, -2, v186
	v_cmp_eq_u32_e32 vcc, s88, v187
	s_and_saveexec_b64 s[28:29], vcc
	v_mul_lo_u32 v186, v186, s87
	v_mov_b32_e32 v187, v173
	v_lshl_add_u64 v[188:189], v[186:187], 2, s[6:7]
	v_lshl_add_u64 v[188:189], v[216:217], 2, v[188:189]
	v_add_co_u32_e32 v188, vcc, 0xf9a26000, v188
	s_nop 1
	v_addc_co_u32_e32 v189, vcc, -1, v189, vcc
	global_store_dwordx4 v[188:189], v[156:159], off offset:-2048
	s_mov_b64 exec, s[28:29]
	v_add_u32_e32 v186, 0x10, v172
	v_and_b32_e32 v187, -2, v186
	v_cmp_eq_u32_e32 vcc, s88, v187
	s_and_saveexec_b64 s[28:29], vcc
	v_mul_lo_u32 v186, v186, s87
	v_mov_b32_e32 v187, v173
	v_lshl_add_u64 v[188:189], v[186:187], 2, s[6:7]
	v_lshl_add_u64 v[188:189], v[216:217], 2, v[188:189]
	v_add_co_u32_e32 v188, vcc, 0xf9a26000, v188
	s_nop 1
	v_addc_co_u32_e32 v189, vcc, -1, v189, vcc
	global_store_dwordx4 v[188:189], v[148:151], off offset:-2048
	s_mov_b64 exec, s[28:29]
	v_add_u32_e32 v186, 0x20, v172
	v_and_b32_e32 v187, -2, v186
	v_cmp_eq_u32_e32 vcc, s88, v187
	s_and_saveexec_b64 s[28:29], vcc
	v_mul_lo_u32 v186, v186, s87
	v_mov_b32_e32 v187, v173
	v_lshl_add_u64 v[188:189], v[186:187], 2, s[6:7]
	v_lshl_add_u64 v[188:189], v[216:217], 2, v[188:189]
	v_add_co_u32_e32 v188, vcc, 0xf9a26000, v188
	s_nop 1
	v_addc_co_u32_e32 v189, vcc, -1, v189, vcc
	global_store_dwordx4 v[188:189], v[140:143], off offset:-2048
	s_mov_b64 exec, s[28:29]
	v_add_u32_e32 v186, 0x30, v172
	v_and_b32_e32 v187, -2, v186
	v_cmp_eq_u32_e32 vcc, s88, v187
	s_and_saveexec_b64 s[28:29], vcc
	v_mul_lo_u32 v186, v186, s87
	v_mov_b32_e32 v187, v173
	v_lshl_add_u64 v[188:189], v[186:187], 2, s[6:7]
	v_lshl_add_u64 v[188:189], v[216:217], 2, v[188:189]
	v_add_co_u32_e32 v188, vcc, 0xf9a26000, v188
	s_nop 1
	v_addc_co_u32_e32 v189, vcc, -1, v189, vcc
	global_store_dwordx4 v[188:189], v[116:119], off offset:-2048
	s_mov_b64 exec, s[28:29]
	v_add_u32_e32 v186, 0x80, v172
	v_and_b32_e32 v187, -2, v186
	v_cmp_eq_u32_e32 vcc, s88, v187
	s_and_saveexec_b64 s[28:29], vcc
	v_mul_lo_u32 v186, v186, s87
	v_mov_b32_e32 v187, v173
	v_lshl_add_u64 v[188:189], v[186:187], 2, s[6:7]
	v_lshl_add_u64 v[188:189], v[216:217], 2, v[188:189]
	v_add_co_u32_e32 v188, vcc, 0xf9a26000, v188
	s_nop 1
	v_addc_co_u32_e32 v189, vcc, -1, v189, vcc
	global_store_dwordx4 v[188:189], v[108:111], off offset:-2048
	s_mov_b64 exec, s[28:29]
	v_add_u32_e32 v186, 0x90, v172
	v_and_b32_e32 v187, -2, v186
	v_cmp_eq_u32_e32 vcc, s88, v187
	s_and_saveexec_b64 s[28:29], vcc
	v_mul_lo_u32 v186, v186, s87
	v_mov_b32_e32 v187, v173
; DI u32x2 pk4(f32x4 v) { u32x2 r; r.x = pk2(v[0], v[1]); r.y = pk2(v[2], v[3]); return r; }
;     DI void operator()(const AccT& acc, const Unit& u, int wr, int wc, int fr, int fq, LAS unsigned char* ldsx) const {
;     ...
;                     const int tok = tok0 + 128 * ai + 16 * m;
;                     bool ok = true;
;                     if (prompt && ai == 0 && m == 0) ok = (64 * wr + fr) >= 2;
;                     if (lastT) ok = ok && tok < SEQ;
;                     if (ok) *(u32x2*)(Y + ((unsigned)tok * (unsigned)DFF + (unsigned)f)) = pk4(y);
;                     if (lastT) { if (tok == SEQ - 2 || tok == SEQ - 1) *(f32x4*)(out + OFF_CVP + (size_t)(tok - (SEQ - 2)) * DFF + f) = g; }
;                     if (!prompt && m == 3 && fr >= 14) *(f32x4*)(out + OFF_CVS + (size_t)(sb * 2 + (fr - 14)) * DFF + f) = g;
;                 }
	v_lshl_add_u64 v[188:189], v[186:187], 2, s[6:7]
	v_lshl_add_u64 v[188:189], v[216:217], 2, v[188:189]
	v_add_co_u32_e32 v188, vcc, 0xf9a26000, v188
	s_nop 1
	v_addc_co_u32_e32 v189, vcc, -1, v189, vcc
	global_store_dwordx4 v[188:189], v[100:103], off offset:-2048
	s_mov_b64 exec, s[28:29]
	v_add_u32_e32 v186, 0xa0, v172
	v_and_b32_e32 v187, -2, v186
	v_cmp_eq_u32_e32 vcc, s88, v187
	s_and_saveexec_b64 s[28:29], vcc
	v_mul_lo_u32 v186, v186, s87
	v_mov_b32_e32 v187, v173
	v_lshl_add_u64 v[188:189], v[186:187], 2, s[6:7]
	v_lshl_add_u64 v[188:189], v[216:217], 2, v[188:189]
	v_add_co_u32_e32 v188, vcc, 0xf9a26000, v188
	s_nop 1
	v_addc_co_u32_e32 v189, vcc, -1, v189, vcc
	global_store_dwordx4 v[188:189], v[92:95], off offset:-2048
	s_mov_b64 exec, s[28:29]
	v_add_u32_e32 v186, 0xb0, v172
	v_and_b32_e32 v187, -2, v186
	v_cmp_eq_u32_e32 vcc, s88, v187
	s_and_saveexec_b64 s[28:29], vcc
	v_mul_lo_u32 v186, v186, s87
	v_mov_b32_e32 v187, v173
	v_lshl_add_u64 v[188:189], v[186:187], 2, s[6:7]
	v_lshl_add_u64 v[188:189], v[216:217], 2, v[188:189]
	v_add_co_u32_e32 v188, vcc, 0xf9a26000, v188
	s_nop 1
	v_addc_co_u32_e32 v189, vcc, -1, v189, vcc
	global_store_dwordx4 v[188:189], v[84:87], off offset:-2048
	s_mov_b64 exec, s[28:29]
	v_mov_b32_e32 v186, v172
	v_and_b32_e32 v187, -2, v186
	v_cmp_eq_u32_e32 vcc, s88, v187
	s_and_saveexec_b64 s[28:29], vcc
	v_mul_lo_u32 v186, v186, s87
	v_mov_b32_e32 v187, v173
	v_lshl_add_u64 v[188:189], v[186:187], 2, s[6:7]
	v_lshl_add_u64 v[188:189], v[182:183], 2, v[188:189]
	v_add_co_u32_e32 v188, vcc, 0xf9a26000, v188
	s_nop 1
	v_addc_co_u32_e32 v189, vcc, -1, v189, vcc
	global_store_dwordx4 v[188:189], v[76:79], off offset:-2048
	s_mov_b64 exec, s[28:29]
	v_add_u32_e32 v186, 0x10, v172
	v_and_b32_e32 v187, -2, v186
	v_cmp_eq_u32_e32 vcc, s88, v187
	s_and_saveexec_b64 s[28:29], vcc
	v_mul_lo_u32 v186, v186, s87
	v_mov_b32_e32 v187, v173
	v_lshl_add_u64 v[188:189], v[186:187], 2, s[6:7]
	v_lshl_add_u64 v[188:189], v[182:183], 2, v[188:189]
	v_add_co_u32_e32 v188, vcc, 0xf9a26000, v188
	s_nop 1
	v_addc_co_u32_e32 v189, vcc, -1, v189, vcc
	global_store_dwordx4 v[188:189], v[68:71], off offset:-2048
	s_mov_b64 exec, s[28:29]
	v_add_u32_e32 v186, 0x20, v172
	v_and_b32_e32 v187, -2, v186
	v_cmp_eq_u32_e32 vcc, s88, v187
	s_and_saveexec_b64 s[28:29], vcc
	v_mul_lo_u32 v186, v186, s87
	v_mov_b32_e32 v187, v173
	v_lshl_add_u64 v[188:189], v[186:187], 2, s[6:7]
	v_lshl_add_u64 v[188:189], v[182:183], 2, v[188:189]
	v_add_co_u32_e32 v188, vcc, 0xf9a26000, v188
	s_nop 1
	v_addc_co_u32_e32 v189, vcc, -1, v189, vcc
	global_store_dwordx4 v[188:189], v[60:63], off offset:-2048
	s_mov_b64 exec, s[28:29]
	v_add_u32_e32 v186, 0x30, v172
	v_and_b32_e32 v187, -2, v186
	v_cmp_eq_u32_e32 vcc, s88, v187
	s_and_saveexec_b64 s[28:29], vcc
	v_mul_lo_u32 v186, v186, s87
	v_mov_b32_e32 v187, v173
	v_lshl_add_u64 v[188:189], v[186:187], 2, s[6:7]
	v_lshl_add_u64 v[188:189], v[182:183], 2, v[188:189]
	v_add_co_u32_e32 v188, vcc, 0xf9a26000, v188
	s_nop 1
	v_addc_co_u32_e32 v189, vcc, -1, v189, vcc
	global_store_dwordx4 v[188:189], v[36:39], off offset:-2048
	s_mov_b64 exec, s[28:29]
	v_add_u32_e32 v186, 0x80, v172
	v_and_b32_e32 v187, -2, v186
	v_cmp_eq_u32_e32 vcc, s88, v187
	s_and_saveexec_b64 s[28:29], vcc
	v_mul_lo_u32 v186, v186, s87
	v_mov_b32_e32 v187, v173
	v_lshl_add_u64 v[188:189], v[186:187], 2, s[6:7]
	v_lshl_add_u64 v[188:189], v[182:183], 2, v[188:189]
	v_add_co_u32_e32 v188, vcc, 0xf9a26000, v188
	s_nop 1
	v_addc_co_u32_e32 v189, vcc, -1, v189, vcc
	global_store_dwordx4 v[188:189], v[28:31], off offset:-2048
	s_mov_b64 exec, s[28:29]
	v_add_u32_e32 v186, 0x90, v172
	v_and_b32_e32 v187, -2, v186
	v_cmp_eq_u32_e32 vcc, s88, v187
	s_and_saveexec_b64 s[28:29], vcc
	v_mul_lo_u32 v186, v186, s87
	v_mov_b32_e32 v187, v173
	v_lshl_add_u64 v[188:189], v[186:187], 2, s[6:7]
	v_lshl_add_u64 v[188:189], v[182:183], 2, v[188:189]
	v_add_co_u32_e32 v188, vcc, 0xf9a26000, v188
	s_nop 1
	v_addc_co_u32_e32 v189, vcc, -1, v189, vcc
	global_store_dwordx4 v[188:189], v[20:23], off offset:-2048
	s_mov_b64 exec, s[28:29]
	v_add_u32_e32 v186, 0xa0, v172
	v_and_b32_e32 v187, -2, v186
	v_cmp_eq_u32_e32 vcc, s88, v187
	s_and_saveexec_b64 s[28:29], vcc
	v_mul_lo_u32 v186, v186, s87
	v_mov_b32_e32 v187, v173
	v_lshl_add_u64 v[188:189], v[186:187], 2, s[6:7]
	v_lshl_add_u64 v[188:189], v[182:183], 2, v[188:189]
	v_add_co_u32_e32 v188, vcc, 0xf9a26000, v188
	s_nop 1
	v_addc_co_u32_e32 v189, vcc, -1, v189, vcc
	global_store_dwordx4 v[188:189], v[12:15], off offset:-2048
	s_mov_b64 exec, s[28:29]
	v_add_u32_e32 v186, 0xb0, v172
	v_and_b32_e32 v187, -2, v186
	v_cmp_eq_u32_e32 vcc, s88, v187
	s_and_saveexec_b64 s[28:29], vcc
	v_mul_lo_u32 v186, v186, s87
	v_mov_b32_e32 v187, v173
	v_lshl_add_u64 v[188:189], v[186:187], 2, s[6:7]
	v_lshl_add_u64 v[188:189], v[182:183], 2, v[188:189]
	v_add_co_u32_e32 v188, vcc, 0xf9a26000, v188
	s_nop 1
	v_addc_co_u32_e32 v189, vcc, -1, v189, vcc
	global_store_dwordx4 v[188:189], v[4:7], off offset:-2048
	s_mov_b64 exec, s[28:29]
.Lgu_nocvp:
	s_cmp_eq_u32 s85, s37
	s_mov_b64 s[0:1], -1
	s_cbranch_scc1 .LBB0_816
